# mode-3 epilogue rewritten with batched loads (48 in flight per 4 rows); GEMM residual epilogue loads batched per row-group
# speedup vs baseline: 1.0576x; 1.0239x over previous
; __device__ __forceinline__ float bf2f(bf16_t v) { return __uint_as_float(((unsigned)v) << 16); }
; __device__ __forceinline__ int crow(int r, int hi) { return (r & 3) + 8 * (r >> 2) + 4 * hi; }
; template <int MODE>
; __device__ __forceinline__ void attn_body(const bf16_t* __restrict__ Qb, const bf16_t* __restrict__ Kh, const bf16_t* __restrict__ Vh, int NT, int krel0,
;                                           char* lds, const float* __restrict__ lutg, const AttnEpi& E) {
;     ...
;   float rli[16];
; #pragma unroll
;   for (int r = 0; r < 16; ++r) rli[r] = __builtin_amdgcn_rcpf(li_l[crow(r, hi)]);
;   float* pk0 = E.park; float* pk1 = E.park + 64 * 512;
;   const int rowb = wid * 32;
;   if constexpr (MODE == 0 || MODE == 1) {
; #pragma unroll
;     for (int r = 0; r < 16; ++r) { const int row = rowb + crow(r, hi);
; #pragma unroll
;       for (int d0 = 0; d0 < 4; ++d0) { const int idx = (d0 * 16 + r) * 512 + tid;
;         const float g = bf2f(E.gate[(size_t)row * GW + d0 * 32 + r32]);
;         const float v = o[d0][r] * rli[r] * g;
;         if constexpr (MODE == 0) pk0[idx] = v; else pk0[idx] += v; } }
;   } else if constexpr (MODE == 2) {
; #pragma unroll
;     for (int r = 0; r < 16; ++r)
; #pragma unroll
;       for (int d0 = 0; d0 < 4; ++d0) pk1[(d0 * 16 + r) * 512 + tid] = o[d0][r] * rli[r];
;   } else {
;     float gs[4];
; #pragma unroll
;     for (int d0 = 0; d0 < 4; ++d0) gs[d0] = E.gsub[d0 * 32 + r32] * E.oml;
; #pragma unroll
;     for (int r = 0; r < 16; ++r) { const int row = rowb + crow(r, hi);
;       float ss = 0.f;
; #pragma unroll
;       for (int d0 = 0; d0 < 4; ++d0) { const float c = pk1[(d0 * 16 + r) * 512 + tid] - E.lam * (o[d0][r] * rli[r]); o[d0][r] = c; ss += c * c; }
;       ss += __shfl_xor(ss, 1); ss += __shfl_xor(ss, 2); ss += __shfl_xor(ss, 4); ss += __shfl_xor(ss, 8); ss += __shfl_xor(ss, 16);
;       const float rs = rsqrtf(ss * (1.f / 128.f) + EPS);
; #pragma unroll
;       for (int d0 = 0; d0 < 4; ++d0) { const int col = d0 * 32 + r32;
;         const float g = bf2f(E.gate[(size_t)row * GW + col]);
;         const float y = o[d0][r] * rs * gs[d0] * g + pk0[(d0 * 16 + r) * 512 + tid];
.LBB0_73:
	s_or_b64 exec, exec, s[0:1]
	s_waitcnt lgkmcnt(0)
	ds_read_b128 v[82:85], v210
	ds_read_b128 v[86:89], v210 offset:32
	ds_read_b128 v[90:93], v210 offset:64
	ds_read_b128 v[94:97], v210 offset:96
	s_add_u32 s0, s56, 0x1000
	s_addc_u32 s1, s57, 0
	s_lshl_b64 s[6:7], s[54:55], 11
	v_readlane_b32 s54, v253, 47
	v_readlane_b32 s55, v253, 48
	s_nop 3
	s_add_u32 s2, s54, s6
	s_addc_u32 s7, s55, s7
	v_readlane_b32 s54, v255, 5
	v_readlane_b32 s55, v255, 6
	s_add_u32 s6, s2, s16
	s_addc_u32 s7, s7, 0
	s_brev_b32 s2, 60
	s_add_i32 s10, s10, s14
	s_add_i32 s93, s93, s14
	v_lshlrev_b32_e32 v109, 2, v184
	s_nop 1
	global_load_dword v98, v109, s[54:55]
	global_load_dword v99, v109, s[54:55] offset:128
	global_load_dword v100, v109, s[54:55] offset:256
	global_load_dword v101, v109, s[54:55] offset:384
	v_lshlrev_b32_e32 v107, 2, v188
	v_or_b32_e32 v108, v205, v204
	v_lshlrev_b32_e32 v164, 1, v184
	v_mov_b32_e32 v165, 0
	v_mov_b32_e32 v110, 0x358637bd
	v_lshl_add_u64 v[162:163], s[0:1], 0, v[164:165]
	v_and_b32_e32 v111, 64, v196
	v_add_u32_e32 v111, 64, v111
	v_xor_b32_e32 v160, 1, v196
	v_cmp_lt_i32_e32 vcc, v160, v111
	s_nop 1
	v_cndmask_b32_e32 v160, v196, v160, vcc
	v_lshlrev_b32_e32 v102, 2, v160
	v_xor_b32_e32 v160, 2, v196
	v_cmp_lt_i32_e32 vcc, v160, v111
	s_nop 1
	v_cndmask_b32_e32 v160, v196, v160, vcc
	v_lshlrev_b32_e32 v103, 2, v160
	v_xor_b32_e32 v160, 4, v196
	v_cmp_lt_i32_e32 vcc, v160, v111
	s_nop 1
	v_cndmask_b32_e32 v160, v196, v160, vcc
	v_lshlrev_b32_e32 v104, 2, v160
	v_xor_b32_e32 v160, 8, v196
	v_cmp_lt_i32_e32 vcc, v160, v111
	s_nop 1
	v_cndmask_b32_e32 v160, v196, v160, vcc
	v_lshlrev_b32_e32 v105, 2, v160
	v_xor_b32_e32 v160, 16, v196
	v_cmp_lt_i32_e32 vcc, v160, v111
	s_nop 1
	v_cndmask_b32_e32 v160, v196, v160, vcc
	v_lshlrev_b32_e32 v106, 2, v160
	s_waitcnt lgkmcnt(0)
	v_rcp_f32_e32 v66, v82
	v_rcp_f32_e32 v67, v83
	v_rcp_f32_e32 v68, v84
	v_rcp_f32_e32 v69, v85
	v_rcp_f32_e32 v70, v86
	v_rcp_f32_e32 v71, v87
	v_rcp_f32_e32 v72, v88
	v_rcp_f32_e32 v73, v89
	v_rcp_f32_e32 v74, v90
	v_rcp_f32_e32 v75, v91
	v_rcp_f32_e32 v76, v92
	v_rcp_f32_e32 v77, v93
	v_rcp_f32_e32 v78, v94
	v_rcp_f32_e32 v79, v95
	v_rcp_f32_e32 v80, v96
	v_rcp_f32_e32 v81, v97
	s_waitcnt vmcnt(0)
	v_mul_f32_e32 v98, v185, v98
	v_mul_f32_e32 v99, v185, v99
	v_mul_f32_e32 v100, v185, v100
	v_mul_f32_e32 v101, v185, v101
	v_add_u32_e32 v166, 0x0, v107
	v_add_u32_e32 v167, 0x8000, v107
	v_add_u32_e32 v168, 0x10000, v107
	v_add_u32_e32 v169, 0x18000, v107
	v_add_u32_e32 v170, 0x1000, v107
	v_add_u32_e32 v171, 0x9000, v107
	v_add_u32_e32 v172, 0x11000, v107
	v_add_u32_e32 v173, 0x19000, v107
	global_load_dword v112, v166, s[36:37]
	global_load_dword v113, v167, s[36:37]
	global_load_dword v114, v168, s[36:37]
	global_load_dword v115, v169, s[36:37]
	global_load_dword v116, v166, s[36:37] offset:2048
	global_load_dword v117, v167, s[36:37] offset:2048
	global_load_dword v118, v168, s[36:37] offset:2048
	global_load_dword v119, v169, s[36:37] offset:2048
	global_load_dword v120, v170, s[36:37]
	global_load_dword v121, v171, s[36:37]
	global_load_dword v122, v172, s[36:37]
	global_load_dword v123, v173, s[36:37]
	global_load_dword v124, v170, s[36:37] offset:2048
	global_load_dword v125, v171, s[36:37] offset:2048
	global_load_dword v126, v172, s[36:37] offset:2048
	global_load_dword v127, v173, s[36:37] offset:2048
	v_mad_i64_i32 v[190:191], s[28:29], v108, s88, v[162:163]
	global_load_ushort v128, v[190:191], off
	global_load_ushort v129, v[190:191], off offset:64
	global_load_ushort v130, v[190:191], off offset:128
	global_load_ushort v131, v[190:191], off offset:192
	v_or_b32_e32 v160, 1, v108
	v_mad_i64_i32 v[190:191], s[28:29], v160, s88, v[162:163]
	global_load_ushort v132, v[190:191], off
	global_load_ushort v133, v[190:191], off offset:64
	global_load_ushort v134, v[190:191], off offset:128
	global_load_ushort v135, v[190:191], off offset:192
	v_or_b32_e32 v160, 2, v108
	v_mad_i64_i32 v[190:191], s[28:29], v160, s88, v[162:163]
	global_load_ushort v136, v[190:191], off
	global_load_ushort v137, v[190:191], off offset:64
	global_load_ushort v138, v[190:191], off offset:128
	global_load_ushort v139, v[190:191], off offset:192
	v_or_b32_e32 v160, 3, v108
	v_mad_i64_i32 v[190:191], s[28:29], v160, s88, v[162:163]
	global_load_ushort v140, v[190:191], off
	global_load_ushort v141, v[190:191], off offset:64
	global_load_ushort v142, v[190:191], off offset:128
	global_load_ushort v143, v[190:191], off offset:192
	global_load_dword v144, v166, s[34:35]
	global_load_dword v145, v167, s[34:35]
	global_load_dword v146, v168, s[34:35]
	global_load_dword v147, v169, s[34:35]
	global_load_dword v148, v166, s[34:35] offset:2048
	global_load_dword v149, v167, s[34:35] offset:2048
	global_load_dword v150, v168, s[34:35] offset:2048
	global_load_dword v151, v169, s[34:35] offset:2048
	global_load_dword v152, v170, s[34:35]
	global_load_dword v153, v171, s[34:35]
	global_load_dword v154, v172, s[34:35]
	global_load_dword v155, v173, s[34:35]
	global_load_dword v156, v170, s[34:35] offset:2048
	global_load_dword v157, v171, s[34:35] offset:2048
	global_load_dword v158, v172, s[34:35] offset:2048
	global_load_dword v159, v173, s[34:35] offset:2048
	s_waitcnt vmcnt(32)
; __device__ __forceinline__ int crow(int r, int hi) { return (r & 3) + 8 * (r >> 2) + 4 * hi; }
; template <int MODE>
; __device__ __forceinline__ void attn_body(const bf16_t* __restrict__ Qb, const bf16_t* __restrict__ Kh, const bf16_t* __restrict__ Vh, int NT, int krel0,
;                                           char* lds, const float* __restrict__ lutg, const AttnEpi& E) {
;     ...
;     for (int r = 0; r < 16; ++r) { const int row = rowb + crow(r, hi);
;       float ss = 0.f;
; #pragma unroll
;       for (int d0 = 0; d0 < 4; ++d0) { const float c = pk1[(d0 * 16 + r) * 512 + tid] - E.lam * (o[d0][r] * rli[r]); o[d0][r] = c; ss += c * c; }
;       ss += __shfl_xor(ss, 1); ss += __shfl_xor(ss, 2); ss += __shfl_xor(ss, 4); ss += __shfl_xor(ss, 8); ss += __shfl_xor(ss, 16);
;       const float rs = rsqrtf(ss * (1.f / 128.f) + EPS);
	v_mul_f32_e32 v50, v50, v66
	v_fma_f32 v112, -v186, v50, v112
	v_mul_f32_e32 v34, v34, v66
	v_fma_f32 v113, -v186, v34, v113
	v_mul_f32_e32 v18, v18, v66
	v_fma_f32 v114, -v186, v18, v114
	v_mul_f32_e32 v2, v2, v66
	v_fma_f32 v115, -v186, v2, v115
	v_mul_f32_e32 v174, v112, v112
	v_mul_f32_e32 v161, v113, v113
	v_add_f32_e32 v174, v174, v161
	v_mul_f32_e32 v161, v114, v114
	v_add_f32_e32 v174, v174, v161
	v_mul_f32_e32 v161, v115, v115
	v_add_f32_e32 v174, v174, v161
	v_mul_f32_e32 v51, v51, v67
	v_fma_f32 v116, -v186, v51, v116
	v_mul_f32_e32 v35, v35, v67
	v_fma_f32 v117, -v186, v35, v117
	v_mul_f32_e32 v19, v19, v67
	v_fma_f32 v118, -v186, v19, v118
	v_mul_f32_e32 v3, v3, v67
	v_fma_f32 v119, -v186, v3, v119
	v_mul_f32_e32 v175, v116, v116
	v_mul_f32_e32 v161, v117, v117
	v_add_f32_e32 v175, v175, v161
	v_mul_f32_e32 v161, v118, v118
	v_add_f32_e32 v175, v175, v161
	v_mul_f32_e32 v161, v119, v119
	v_add_f32_e32 v175, v175, v161
	v_mul_f32_e32 v52, v52, v68
	v_fma_f32 v120, -v186, v52, v120
	v_mul_f32_e32 v36, v36, v68
	v_fma_f32 v121, -v186, v36, v121
	v_mul_f32_e32 v20, v20, v68
	v_fma_f32 v122, -v186, v20, v122
	v_mul_f32_e32 v4, v4, v68
	v_fma_f32 v123, -v186, v4, v123
	v_mul_f32_e32 v176, v120, v120
	v_mul_f32_e32 v161, v121, v121
	v_add_f32_e32 v176, v176, v161
	v_mul_f32_e32 v161, v122, v122
	v_add_f32_e32 v176, v176, v161
	v_mul_f32_e32 v161, v123, v123
	v_add_f32_e32 v176, v176, v161
	v_mul_f32_e32 v53, v53, v69
	v_fma_f32 v124, -v186, v53, v124
	v_mul_f32_e32 v37, v37, v69
	v_fma_f32 v125, -v186, v37, v125
	v_mul_f32_e32 v21, v21, v69
	v_fma_f32 v126, -v186, v21, v126
	v_mul_f32_e32 v5, v5, v69
	v_fma_f32 v127, -v186, v5, v127
	v_mul_f32_e32 v177, v124, v124
	v_mul_f32_e32 v161, v125, v125
	v_add_f32_e32 v177, v177, v161
	v_mul_f32_e32 v161, v126, v126
	v_add_f32_e32 v177, v177, v161
	v_mul_f32_e32 v161, v127, v127
	v_add_f32_e32 v177, v177, v161
	ds_bpermute_b32 v194, v102, v174
	ds_bpermute_b32 v195, v102, v175
	ds_bpermute_b32 v206, v102, v176
	ds_bpermute_b32 v207, v102, v177
	s_waitcnt lgkmcnt(0)
	v_add_f32_e32 v174, v174, v194
	v_add_f32_e32 v175, v175, v195
	v_add_f32_e32 v176, v176, v206
	v_add_f32_e32 v177, v177, v207
	ds_bpermute_b32 v194, v103, v174
	ds_bpermute_b32 v195, v103, v175
	ds_bpermute_b32 v206, v103, v176
	ds_bpermute_b32 v207, v103, v177
	s_waitcnt lgkmcnt(0)
	v_add_f32_e32 v174, v174, v194
	v_add_f32_e32 v175, v175, v195
	v_add_f32_e32 v176, v176, v206
	v_add_f32_e32 v177, v177, v207
	ds_bpermute_b32 v194, v104, v174
	ds_bpermute_b32 v195, v104, v175
	ds_bpermute_b32 v206, v104, v176
	ds_bpermute_b32 v207, v104, v177
	s_waitcnt lgkmcnt(0)
	v_add_f32_e32 v174, v174, v194
	v_add_f32_e32 v175, v175, v195
	v_add_f32_e32 v176, v176, v206
	v_add_f32_e32 v177, v177, v207
	ds_bpermute_b32 v194, v105, v174
	ds_bpermute_b32 v195, v105, v175
	ds_bpermute_b32 v206, v105, v176
	ds_bpermute_b32 v207, v105, v177
	s_waitcnt lgkmcnt(0)
	v_add_f32_e32 v174, v174, v194
	v_add_f32_e32 v175, v175, v195
	v_add_f32_e32 v176, v176, v206
	v_add_f32_e32 v177, v177, v207
	ds_bpermute_b32 v194, v106, v174
	ds_bpermute_b32 v195, v106, v175
	ds_bpermute_b32 v206, v106, v176
	ds_bpermute_b32 v207, v106, v177
	s_waitcnt lgkmcnt(0)
	v_add_f32_e32 v174, v174, v194
	v_add_f32_e32 v175, v175, v195
	v_add_f32_e32 v176, v176, v206
	v_add_f32_e32 v177, v177, v207
	v_fma_f32 v174, v174, s2, v110
	v_mul_f32_e32 v161, 0x4b800000, v174
	v_cmp_gt_f32_e32 vcc, s49, v174
	s_nop 1
	v_cndmask_b32_e32 v174, v174, v161, vcc
	v_rsq_f32_e32 v174, v174
	s_nop 0
	v_mul_f32_e32 v161, 0x45800000, v174
	v_cndmask_b32_e32 v174, v174, v161, vcc
	v_fma_f32 v175, v175, s2, v110
	v_mul_f32_e32 v161, 0x4b800000, v175
	v_cmp_gt_f32_e32 vcc, s49, v175
	s_nop 1
	v_cndmask_b32_e32 v175, v175, v161, vcc
	v_rsq_f32_e32 v175, v175
	s_nop 0
	v_mul_f32_e32 v161, 0x45800000, v175
	v_cndmask_b32_e32 v175, v175, v161, vcc
	v_fma_f32 v176, v176, s2, v110
	v_mul_f32_e32 v161, 0x4b800000, v176
	v_cmp_gt_f32_e32 vcc, s49, v176
	s_nop 1
	v_cndmask_b32_e32 v176, v176, v161, vcc
	v_rsq_f32_e32 v176, v176
	s_nop 0
	v_mul_f32_e32 v161, 0x45800000, v176
	v_cndmask_b32_e32 v176, v176, v161, vcc
	v_fma_f32 v177, v177, s2, v110
	v_mul_f32_e32 v161, 0x4b800000, v177
	v_cmp_gt_f32_e32 vcc, s49, v177
	s_nop 1
	v_cndmask_b32_e32 v177, v177, v161, vcc
	v_rsq_f32_e32 v177, v177
	s_nop 0
	v_mul_f32_e32 v161, 0x45800000, v177
	v_cndmask_b32_e32 v177, v177, v161, vcc
	s_waitcnt vmcnt(0)
; __device__ __forceinline__ unsigned cvtpk(float lo, float hi) { f32x2 v = {lo, hi}; bf16v2 b = __builtin_convertvector(v, bf16v2); return __builtin_bit_cast(unsigned, b); }
; __device__ __forceinline__ float bf2f(bf16_t v) { return __uint_as_float(((unsigned)v) << 16); }
; template <int MODE>
; __device__ __forceinline__ void attn_body(const bf16_t* __restrict__ Qb, const bf16_t* __restrict__ Kh, const bf16_t* __restrict__ Vh, int NT, int krel0,
;                                           char* lds, const float* __restrict__ lutg, const AttnEpi& E) {
;     ...
;       for (int d0 = 0; d0 < 4; ++d0) { const float c = pk1[(d0 * 16 + r) * 512 + tid] - E.lam * (o[d0][r] * rli[r]); o[d0][r] = c; ss += c * c; }
;       ss += __shfl_xor(ss, 1); ss += __shfl_xor(ss, 2); ss += __shfl_xor(ss, 4); ss += __shfl_xor(ss, 8); ss += __shfl_xor(ss, 16);
;       const float rs = rsqrtf(ss * (1.f / 128.f) + EPS);
; #pragma unroll
;       for (int d0 = 0; d0 < 4; ++d0) { const int col = d0 * 32 + r32;
;         const float g = bf2f(E.gate[(size_t)row * GW + col]);
;         const float y = o[d0][r] * rs * gs[d0] * g + pk0[(d0 * 16 + r) * 512 + tid];
;         E.merged[(size_t)row * DM + col] = (bf16_t)(cvtpk(y, y) & 0xffffu); } }
	v_lshl_add_u32 v161, v108, 11, v164
	v_mul_f32_e32 v112, v112, v174
	v_mul_f32_e32 v112, v98, v112
	v_lshlrev_b32_e32 v128, 16, v128
	v_fmac_f32_e32 v144, v112, v128
	v_cvt_pk_bf16_f32 v144, v144, v144
	global_store_short v161, v144, s[6:7]
	v_mul_f32_e32 v113, v113, v174
	v_mul_f32_e32 v113, v99, v113
	v_lshlrev_b32_e32 v129, 16, v129
	v_fmac_f32_e32 v145, v113, v129
	v_cvt_pk_bf16_f32 v145, v145, v145
	global_store_short v161, v145, s[6:7] offset:64
	v_mul_f32_e32 v114, v114, v174
	v_mul_f32_e32 v114, v100, v114
	v_lshlrev_b32_e32 v130, 16, v130
	v_fmac_f32_e32 v146, v114, v130
	v_cvt_pk_bf16_f32 v146, v146, v146
	global_store_short v161, v146, s[6:7] offset:128
	v_mul_f32_e32 v115, v115, v174
	v_mul_f32_e32 v115, v101, v115
	v_lshlrev_b32_e32 v131, 16, v131
	v_fmac_f32_e32 v147, v115, v131
	v_cvt_pk_bf16_f32 v147, v147, v147
	global_store_short v161, v147, s[6:7] offset:192
	v_or_b32_e32 v160, 1, v108
	v_lshl_add_u32 v161, v160, 11, v164
	v_mul_f32_e32 v116, v116, v175
	v_mul_f32_e32 v116, v98, v116
	v_lshlrev_b32_e32 v132, 16, v132
	v_fmac_f32_e32 v148, v116, v132
	v_cvt_pk_bf16_f32 v148, v148, v148
	global_store_short v161, v148, s[6:7]
	v_mul_f32_e32 v117, v117, v175
	v_mul_f32_e32 v117, v99, v117
	v_lshlrev_b32_e32 v133, 16, v133
	v_fmac_f32_e32 v149, v117, v133
	v_cvt_pk_bf16_f32 v149, v149, v149
	global_store_short v161, v149, s[6:7] offset:64
	v_mul_f32_e32 v118, v118, v175
	v_mul_f32_e32 v118, v100, v118
	v_lshlrev_b32_e32 v134, 16, v134
	v_fmac_f32_e32 v150, v118, v134
	v_cvt_pk_bf16_f32 v150, v150, v150
	global_store_short v161, v150, s[6:7] offset:128
	v_mul_f32_e32 v119, v119, v175
	v_mul_f32_e32 v119, v101, v119
	v_lshlrev_b32_e32 v135, 16, v135
	v_fmac_f32_e32 v151, v119, v135
	v_cvt_pk_bf16_f32 v151, v151, v151
	global_store_short v161, v151, s[6:7] offset:192
	v_or_b32_e32 v160, 2, v108
	v_lshl_add_u32 v161, v160, 11, v164
	v_mul_f32_e32 v120, v120, v176
	v_mul_f32_e32 v120, v98, v120
	v_lshlrev_b32_e32 v136, 16, v136
	v_fmac_f32_e32 v152, v120, v136
	v_cvt_pk_bf16_f32 v152, v152, v152
	global_store_short v161, v152, s[6:7]
	v_mul_f32_e32 v121, v121, v176
	v_mul_f32_e32 v121, v99, v121
	v_lshlrev_b32_e32 v137, 16, v137
	v_fmac_f32_e32 v153, v121, v137
	v_cvt_pk_bf16_f32 v153, v153, v153
	global_store_short v161, v153, s[6:7] offset:64
	v_mul_f32_e32 v122, v122, v176
	v_mul_f32_e32 v122, v100, v122
	v_lshlrev_b32_e32 v138, 16, v138
	v_fmac_f32_e32 v154, v122, v138
	v_cvt_pk_bf16_f32 v154, v154, v154
	global_store_short v161, v154, s[6:7] offset:128
	v_mul_f32_e32 v123, v123, v176
	v_mul_f32_e32 v123, v101, v123
	v_lshlrev_b32_e32 v139, 16, v139
	v_fmac_f32_e32 v155, v123, v139
	v_cvt_pk_bf16_f32 v155, v155, v155
	global_store_short v161, v155, s[6:7] offset:192
	v_or_b32_e32 v160, 3, v108
	v_lshl_add_u32 v161, v160, 11, v164
	v_mul_f32_e32 v124, v124, v177
	v_mul_f32_e32 v124, v98, v124
	v_lshlrev_b32_e32 v140, 16, v140
	v_fmac_f32_e32 v156, v124, v140
	v_cvt_pk_bf16_f32 v156, v156, v156
	global_store_short v161, v156, s[6:7]
	v_mul_f32_e32 v125, v125, v177
	v_mul_f32_e32 v125, v99, v125
	v_lshlrev_b32_e32 v141, 16, v141
	v_fmac_f32_e32 v157, v125, v141
	v_cvt_pk_bf16_f32 v157, v157, v157
	global_store_short v161, v157, s[6:7] offset:64
	v_mul_f32_e32 v126, v126, v177
	v_mul_f32_e32 v126, v100, v126
	v_lshlrev_b32_e32 v142, 16, v142
	v_fmac_f32_e32 v158, v126, v142
	v_cvt_pk_bf16_f32 v158, v158, v158
	global_store_short v161, v158, s[6:7] offset:128
	v_mul_f32_e32 v127, v127, v177
	v_mul_f32_e32 v127, v101, v127
	v_lshlrev_b32_e32 v143, 16, v143
	v_fmac_f32_e32 v159, v127, v143
	v_cvt_pk_bf16_f32 v159, v159, v159
	global_store_short v161, v159, s[6:7] offset:192
	v_add_u32_e32 v166, 0x2000, v107
	v_add_u32_e32 v167, 0xa000, v107
	v_add_u32_e32 v168, 0x12000, v107
	v_add_u32_e32 v169, 0x1a000, v107
	v_add_u32_e32 v170, 0x3000, v107
	v_add_u32_e32 v171, 0xb000, v107
	v_add_u32_e32 v172, 0x13000, v107
	v_add_u32_e32 v173, 0x1b000, v107
	global_load_dword v112, v166, s[36:37]
	global_load_dword v113, v167, s[36:37]
	global_load_dword v114, v168, s[36:37]
	global_load_dword v115, v169, s[36:37]
	global_load_dword v116, v166, s[36:37] offset:2048
	global_load_dword v117, v167, s[36:37] offset:2048
	global_load_dword v118, v168, s[36:37] offset:2048
	global_load_dword v119, v169, s[36:37] offset:2048
	global_load_dword v120, v170, s[36:37]
	global_load_dword v121, v171, s[36:37]
	global_load_dword v122, v172, s[36:37]
	global_load_dword v123, v173, s[36:37]
	global_load_dword v124, v170, s[36:37] offset:2048
	global_load_dword v125, v171, s[36:37] offset:2048
	global_load_dword v126, v172, s[36:37] offset:2048
	global_load_dword v127, v173, s[36:37] offset:2048
	v_or_b32_e32 v160, 8, v108
	v_mad_i64_i32 v[190:191], s[28:29], v160, s88, v[162:163]
	global_load_ushort v128, v[190:191], off
	global_load_ushort v129, v[190:191], off offset:64
	global_load_ushort v130, v[190:191], off offset:128
	global_load_ushort v131, v[190:191], off offset:192
	v_or_b32_e32 v160, 9, v108
	v_mad_i64_i32 v[190:191], s[28:29], v160, s88, v[162:163]
	global_load_ushort v132, v[190:191], off
	global_load_ushort v133, v[190:191], off offset:64
	global_load_ushort v134, v[190:191], off offset:128
	global_load_ushort v135, v[190:191], off offset:192
	v_or_b32_e32 v160, 10, v108
	v_mad_i64_i32 v[190:191], s[28:29], v160, s88, v[162:163]
	global_load_ushort v136, v[190:191], off
	global_load_ushort v137, v[190:191], off offset:64
	global_load_ushort v138, v[190:191], off offset:128
	global_load_ushort v139, v[190:191], off offset:192
	v_or_b32_e32 v160, 11, v108
	v_mad_i64_i32 v[190:191], s[28:29], v160, s88, v[162:163]
	global_load_ushort v140, v[190:191], off
	global_load_ushort v141, v[190:191], off offset:64
	global_load_ushort v142, v[190:191], off offset:128
	global_load_ushort v143, v[190:191], off offset:192
	global_load_dword v144, v166, s[34:35]
	global_load_dword v145, v167, s[34:35]
	global_load_dword v146, v168, s[34:35]
	global_load_dword v147, v169, s[34:35]
	global_load_dword v148, v166, s[34:35] offset:2048
	global_load_dword v149, v167, s[34:35] offset:2048
	global_load_dword v150, v168, s[34:35] offset:2048
	global_load_dword v151, v169, s[34:35] offset:2048
	global_load_dword v152, v170, s[34:35]
	global_load_dword v153, v171, s[34:35]
	global_load_dword v154, v172, s[34:35]
	global_load_dword v155, v173, s[34:35]
	global_load_dword v156, v170, s[34:35] offset:2048
	global_load_dword v157, v171, s[34:35] offset:2048
	global_load_dword v158, v172, s[34:35] offset:2048
	global_load_dword v159, v173, s[34:35] offset:2048
	s_waitcnt vmcnt(32)
; __device__ __forceinline__ int crow(int r, int hi) { return (r & 3) + 8 * (r >> 2) + 4 * hi; }
; template <int MODE>
; __device__ __forceinline__ void attn_body(const bf16_t* __restrict__ Qb, const bf16_t* __restrict__ Kh, const bf16_t* __restrict__ Vh, int NT, int krel0,
;                                           char* lds, const float* __restrict__ lutg, const AttnEpi& E) {
;     ...
;     for (int r = 0; r < 16; ++r) { const int row = rowb + crow(r, hi);
;       float ss = 0.f;
; #pragma unroll
;       for (int d0 = 0; d0 < 4; ++d0) { const float c = pk1[(d0 * 16 + r) * 512 + tid] - E.lam * (o[d0][r] * rli[r]); o[d0][r] = c; ss += c * c; }
;       ss += __shfl_xor(ss, 1); ss += __shfl_xor(ss, 2); ss += __shfl_xor(ss, 4); ss += __shfl_xor(ss, 8); ss += __shfl_xor(ss, 16);
;       const float rs = rsqrtf(ss * (1.f / 128.f) + EPS);
	v_mul_f32_e32 v54, v54, v70
	v_fma_f32 v112, -v186, v54, v112
	v_mul_f32_e32 v38, v38, v70
	v_fma_f32 v113, -v186, v38, v113
	v_mul_f32_e32 v22, v22, v70
	v_fma_f32 v114, -v186, v22, v114
	v_mul_f32_e32 v6, v6, v70
	v_fma_f32 v115, -v186, v6, v115
	v_mul_f32_e32 v174, v112, v112
	v_mul_f32_e32 v161, v113, v113
	v_add_f32_e32 v174, v174, v161
	v_mul_f32_e32 v161, v114, v114
	v_add_f32_e32 v174, v174, v161
	v_mul_f32_e32 v161, v115, v115
	v_add_f32_e32 v174, v174, v161
	v_mul_f32_e32 v55, v55, v71
	v_fma_f32 v116, -v186, v55, v116
	v_mul_f32_e32 v39, v39, v71
	v_fma_f32 v117, -v186, v39, v117
	v_mul_f32_e32 v23, v23, v71
	v_fma_f32 v118, -v186, v23, v118
	v_mul_f32_e32 v7, v7, v71
	v_fma_f32 v119, -v186, v7, v119
	v_mul_f32_e32 v175, v116, v116
	v_mul_f32_e32 v161, v117, v117
	v_add_f32_e32 v175, v175, v161
	v_mul_f32_e32 v161, v118, v118
	v_add_f32_e32 v175, v175, v161
	v_mul_f32_e32 v161, v119, v119
	v_add_f32_e32 v175, v175, v161
	v_mul_f32_e32 v56, v56, v72
	v_fma_f32 v120, -v186, v56, v120
	v_mul_f32_e32 v40, v40, v72
	v_fma_f32 v121, -v186, v40, v121
	v_mul_f32_e32 v24, v24, v72
	v_fma_f32 v122, -v186, v24, v122
	v_mul_f32_e32 v8, v8, v72
	v_fma_f32 v123, -v186, v8, v123
	v_mul_f32_e32 v176, v120, v120
	v_mul_f32_e32 v161, v121, v121
	v_add_f32_e32 v176, v176, v161
	v_mul_f32_e32 v161, v122, v122
	v_add_f32_e32 v176, v176, v161
	v_mul_f32_e32 v161, v123, v123
	v_add_f32_e32 v176, v176, v161
	v_mul_f32_e32 v57, v57, v73
	v_fma_f32 v124, -v186, v57, v124
	v_mul_f32_e32 v41, v41, v73
	v_fma_f32 v125, -v186, v41, v125
	v_mul_f32_e32 v25, v25, v73
	v_fma_f32 v126, -v186, v25, v126
	v_mul_f32_e32 v9, v9, v73
	v_fma_f32 v127, -v186, v9, v127
	v_mul_f32_e32 v177, v124, v124
	v_mul_f32_e32 v161, v125, v125
	v_add_f32_e32 v177, v177, v161
	v_mul_f32_e32 v161, v126, v126
	v_add_f32_e32 v177, v177, v161
	v_mul_f32_e32 v161, v127, v127
	v_add_f32_e32 v177, v177, v161
	ds_bpermute_b32 v194, v102, v174
	ds_bpermute_b32 v195, v102, v175
	ds_bpermute_b32 v206, v102, v176
	ds_bpermute_b32 v207, v102, v177
	s_waitcnt lgkmcnt(0)
	v_add_f32_e32 v174, v174, v194
	v_add_f32_e32 v175, v175, v195
	v_add_f32_e32 v176, v176, v206
	v_add_f32_e32 v177, v177, v207
	ds_bpermute_b32 v194, v103, v174
	ds_bpermute_b32 v195, v103, v175
	ds_bpermute_b32 v206, v103, v176
	ds_bpermute_b32 v207, v103, v177
	s_waitcnt lgkmcnt(0)
	v_add_f32_e32 v174, v174, v194
	v_add_f32_e32 v175, v175, v195
	v_add_f32_e32 v176, v176, v206
	v_add_f32_e32 v177, v177, v207
	ds_bpermute_b32 v194, v104, v174
	ds_bpermute_b32 v195, v104, v175
	ds_bpermute_b32 v206, v104, v176
	ds_bpermute_b32 v207, v104, v177
	s_waitcnt lgkmcnt(0)
	v_add_f32_e32 v174, v174, v194
	v_add_f32_e32 v175, v175, v195
	v_add_f32_e32 v176, v176, v206
	v_add_f32_e32 v177, v177, v207
	ds_bpermute_b32 v194, v105, v174
	ds_bpermute_b32 v195, v105, v175
	ds_bpermute_b32 v206, v105, v176
	ds_bpermute_b32 v207, v105, v177
	s_waitcnt lgkmcnt(0)
	v_add_f32_e32 v174, v174, v194
	v_add_f32_e32 v175, v175, v195
	v_add_f32_e32 v176, v176, v206
	v_add_f32_e32 v177, v177, v207
	ds_bpermute_b32 v194, v106, v174
	ds_bpermute_b32 v195, v106, v175
	ds_bpermute_b32 v206, v106, v176
	ds_bpermute_b32 v207, v106, v177
	s_waitcnt lgkmcnt(0)
	v_add_f32_e32 v174, v174, v194
	v_add_f32_e32 v175, v175, v195
	v_add_f32_e32 v176, v176, v206
	v_add_f32_e32 v177, v177, v207
	v_fma_f32 v174, v174, s2, v110
	v_mul_f32_e32 v161, 0x4b800000, v174
	v_cmp_gt_f32_e32 vcc, s49, v174
	s_nop 1
	v_cndmask_b32_e32 v174, v174, v161, vcc
	v_rsq_f32_e32 v174, v174
	s_nop 0
	v_mul_f32_e32 v161, 0x45800000, v174
	v_cndmask_b32_e32 v174, v174, v161, vcc
	v_fma_f32 v175, v175, s2, v110
	v_mul_f32_e32 v161, 0x4b800000, v175
	v_cmp_gt_f32_e32 vcc, s49, v175
	s_nop 1
	v_cndmask_b32_e32 v175, v175, v161, vcc
	v_rsq_f32_e32 v175, v175
	s_nop 0
	v_mul_f32_e32 v161, 0x45800000, v175
	v_cndmask_b32_e32 v175, v175, v161, vcc
	v_fma_f32 v176, v176, s2, v110
	v_mul_f32_e32 v161, 0x4b800000, v176
	v_cmp_gt_f32_e32 vcc, s49, v176
	s_nop 1
	v_cndmask_b32_e32 v176, v176, v161, vcc
	v_rsq_f32_e32 v176, v176
	s_nop 0
	v_mul_f32_e32 v161, 0x45800000, v176
	v_cndmask_b32_e32 v176, v176, v161, vcc
	v_fma_f32 v177, v177, s2, v110
	v_mul_f32_e32 v161, 0x4b800000, v177
	v_cmp_gt_f32_e32 vcc, s49, v177
	s_nop 1
	v_cndmask_b32_e32 v177, v177, v161, vcc
	v_rsq_f32_e32 v177, v177
	s_nop 0
	v_mul_f32_e32 v161, 0x45800000, v177
	v_cndmask_b32_e32 v177, v177, v161, vcc
	s_waitcnt vmcnt(0)
; __device__ __forceinline__ unsigned cvtpk(float lo, float hi) { f32x2 v = {lo, hi}; bf16v2 b = __builtin_convertvector(v, bf16v2); return __builtin_bit_cast(unsigned, b); }
; __device__ __forceinline__ float bf2f(bf16_t v) { return __uint_as_float(((unsigned)v) << 16); }
; template <int MODE>
; __device__ __forceinline__ void attn_body(const bf16_t* __restrict__ Qb, const bf16_t* __restrict__ Kh, const bf16_t* __restrict__ Vh, int NT, int krel0,
;                                           char* lds, const float* __restrict__ lutg, const AttnEpi& E) {
;     ...
;       for (int d0 = 0; d0 < 4; ++d0) { const float c = pk1[(d0 * 16 + r) * 512 + tid] - E.lam * (o[d0][r] * rli[r]); o[d0][r] = c; ss += c * c; }
;       ss += __shfl_xor(ss, 1); ss += __shfl_xor(ss, 2); ss += __shfl_xor(ss, 4); ss += __shfl_xor(ss, 8); ss += __shfl_xor(ss, 16);
;       const float rs = rsqrtf(ss * (1.f / 128.f) + EPS);
; #pragma unroll
;       for (int d0 = 0; d0 < 4; ++d0) { const int col = d0 * 32 + r32;
;         const float g = bf2f(E.gate[(size_t)row * GW + col]);
;         const float y = o[d0][r] * rs * gs[d0] * g + pk0[(d0 * 16 + r) * 512 + tid];
;         E.merged[(size_t)row * DM + col] = (bf16_t)(cvtpk(y, y) & 0xffffu); } }
	v_or_b32_e32 v160, 8, v108
	v_lshl_add_u32 v161, v160, 11, v164
	v_mul_f32_e32 v112, v112, v174
	v_mul_f32_e32 v112, v98, v112
	v_lshlrev_b32_e32 v128, 16, v128
	v_fmac_f32_e32 v144, v112, v128
	v_cvt_pk_bf16_f32 v144, v144, v144
	global_store_short v161, v144, s[6:7]
	v_mul_f32_e32 v113, v113, v174
	v_mul_f32_e32 v113, v99, v113
	v_lshlrev_b32_e32 v129, 16, v129
	v_fmac_f32_e32 v145, v113, v129
	v_cvt_pk_bf16_f32 v145, v145, v145
	global_store_short v161, v145, s[6:7] offset:64
	v_mul_f32_e32 v114, v114, v174
	v_mul_f32_e32 v114, v100, v114
	v_lshlrev_b32_e32 v130, 16, v130
	v_fmac_f32_e32 v146, v114, v130
	v_cvt_pk_bf16_f32 v146, v146, v146
	global_store_short v161, v146, s[6:7] offset:128
	v_mul_f32_e32 v115, v115, v174
	v_mul_f32_e32 v115, v101, v115
	v_lshlrev_b32_e32 v131, 16, v131
	v_fmac_f32_e32 v147, v115, v131
	v_cvt_pk_bf16_f32 v147, v147, v147
	global_store_short v161, v147, s[6:7] offset:192
	v_or_b32_e32 v160, 9, v108
	v_lshl_add_u32 v161, v160, 11, v164
	v_mul_f32_e32 v116, v116, v175
	v_mul_f32_e32 v116, v98, v116
	v_lshlrev_b32_e32 v132, 16, v132
	v_fmac_f32_e32 v148, v116, v132
	v_cvt_pk_bf16_f32 v148, v148, v148
	global_store_short v161, v148, s[6:7]
	v_mul_f32_e32 v117, v117, v175
	v_mul_f32_e32 v117, v99, v117
	v_lshlrev_b32_e32 v133, 16, v133
	v_fmac_f32_e32 v149, v117, v133
	v_cvt_pk_bf16_f32 v149, v149, v149
	global_store_short v161, v149, s[6:7] offset:64
	v_mul_f32_e32 v118, v118, v175
	v_mul_f32_e32 v118, v100, v118
	v_lshlrev_b32_e32 v134, 16, v134
	v_fmac_f32_e32 v150, v118, v134
	v_cvt_pk_bf16_f32 v150, v150, v150
	global_store_short v161, v150, s[6:7] offset:128
	v_mul_f32_e32 v119, v119, v175
	v_mul_f32_e32 v119, v101, v119
	v_lshlrev_b32_e32 v135, 16, v135
	v_fmac_f32_e32 v151, v119, v135
	v_cvt_pk_bf16_f32 v151, v151, v151
	global_store_short v161, v151, s[6:7] offset:192
	v_or_b32_e32 v160, 10, v108
	v_lshl_add_u32 v161, v160, 11, v164
	v_mul_f32_e32 v120, v120, v176
	v_mul_f32_e32 v120, v98, v120
	v_lshlrev_b32_e32 v136, 16, v136
	v_fmac_f32_e32 v152, v120, v136
	v_cvt_pk_bf16_f32 v152, v152, v152
	global_store_short v161, v152, s[6:7]
	v_mul_f32_e32 v121, v121, v176
	v_mul_f32_e32 v121, v99, v121
	v_lshlrev_b32_e32 v137, 16, v137
	v_fmac_f32_e32 v153, v121, v137
	v_cvt_pk_bf16_f32 v153, v153, v153
	global_store_short v161, v153, s[6:7] offset:64
	v_mul_f32_e32 v122, v122, v176
	v_mul_f32_e32 v122, v100, v122
	v_lshlrev_b32_e32 v138, 16, v138
	v_fmac_f32_e32 v154, v122, v138
	v_cvt_pk_bf16_f32 v154, v154, v154
	global_store_short v161, v154, s[6:7] offset:128
	v_mul_f32_e32 v123, v123, v176
	v_mul_f32_e32 v123, v101, v123
	v_lshlrev_b32_e32 v139, 16, v139
	v_fmac_f32_e32 v155, v123, v139
	v_cvt_pk_bf16_f32 v155, v155, v155
	global_store_short v161, v155, s[6:7] offset:192
	v_or_b32_e32 v160, 11, v108
	v_lshl_add_u32 v161, v160, 11, v164
	v_mul_f32_e32 v124, v124, v177
	v_mul_f32_e32 v124, v98, v124
	v_lshlrev_b32_e32 v140, 16, v140
	v_fmac_f32_e32 v156, v124, v140
	v_cvt_pk_bf16_f32 v156, v156, v156
	global_store_short v161, v156, s[6:7]
	v_mul_f32_e32 v125, v125, v177
	v_mul_f32_e32 v125, v99, v125
	v_lshlrev_b32_e32 v141, 16, v141
	v_fmac_f32_e32 v157, v125, v141
	v_cvt_pk_bf16_f32 v157, v157, v157
	global_store_short v161, v157, s[6:7] offset:64
	v_mul_f32_e32 v126, v126, v177
	v_mul_f32_e32 v126, v100, v126
	v_lshlrev_b32_e32 v142, 16, v142
	v_fmac_f32_e32 v158, v126, v142
	v_cvt_pk_bf16_f32 v158, v158, v158
	global_store_short v161, v158, s[6:7] offset:128
	v_mul_f32_e32 v127, v127, v177
	v_mul_f32_e32 v127, v101, v127
	v_lshlrev_b32_e32 v143, 16, v143
	v_fmac_f32_e32 v159, v127, v143
	v_cvt_pk_bf16_f32 v159, v159, v159
	global_store_short v161, v159, s[6:7] offset:192
	v_add_u32_e32 v166, 0x4000, v107
	v_add_u32_e32 v167, 0xc000, v107
	v_add_u32_e32 v168, 0x14000, v107
	v_add_u32_e32 v169, 0x1c000, v107
	v_add_u32_e32 v170, 0x5000, v107
	v_add_u32_e32 v171, 0xd000, v107
	v_add_u32_e32 v172, 0x15000, v107
	v_add_u32_e32 v173, 0x1d000, v107
	global_load_dword v112, v166, s[36:37]
	global_load_dword v113, v167, s[36:37]
	global_load_dword v114, v168, s[36:37]
	global_load_dword v115, v169, s[36:37]
	global_load_dword v116, v166, s[36:37] offset:2048
	global_load_dword v117, v167, s[36:37] offset:2048
	global_load_dword v118, v168, s[36:37] offset:2048
	global_load_dword v119, v169, s[36:37] offset:2048
	global_load_dword v120, v170, s[36:37]
	global_load_dword v121, v171, s[36:37]
	global_load_dword v122, v172, s[36:37]
	global_load_dword v123, v173, s[36:37]
	global_load_dword v124, v170, s[36:37] offset:2048
	global_load_dword v125, v171, s[36:37] offset:2048
	global_load_dword v126, v172, s[36:37] offset:2048
	global_load_dword v127, v173, s[36:37] offset:2048
	v_or_b32_e32 v160, 16, v108
	v_mad_i64_i32 v[190:191], s[28:29], v160, s88, v[162:163]
	global_load_ushort v128, v[190:191], off
	global_load_ushort v129, v[190:191], off offset:64
	global_load_ushort v130, v[190:191], off offset:128
	global_load_ushort v131, v[190:191], off offset:192
	v_or_b32_e32 v160, 17, v108
	v_mad_i64_i32 v[190:191], s[28:29], v160, s88, v[162:163]
	global_load_ushort v132, v[190:191], off
	global_load_ushort v133, v[190:191], off offset:64
	global_load_ushort v134, v[190:191], off offset:128
	global_load_ushort v135, v[190:191], off offset:192
	v_or_b32_e32 v160, 18, v108
	v_mad_i64_i32 v[190:191], s[28:29], v160, s88, v[162:163]
	global_load_ushort v136, v[190:191], off
	global_load_ushort v137, v[190:191], off offset:64
	global_load_ushort v138, v[190:191], off offset:128
	global_load_ushort v139, v[190:191], off offset:192
	v_or_b32_e32 v160, 19, v108
	v_mad_i64_i32 v[190:191], s[28:29], v160, s88, v[162:163]
	global_load_ushort v140, v[190:191], off
	global_load_ushort v141, v[190:191], off offset:64
	global_load_ushort v142, v[190:191], off offset:128
	global_load_ushort v143, v[190:191], off offset:192
	global_load_dword v144, v166, s[34:35]
	global_load_dword v145, v167, s[34:35]
	global_load_dword v146, v168, s[34:35]
	global_load_dword v147, v169, s[34:35]
	global_load_dword v148, v166, s[34:35] offset:2048
	global_load_dword v149, v167, s[34:35] offset:2048
	global_load_dword v150, v168, s[34:35] offset:2048
	global_load_dword v151, v169, s[34:35] offset:2048
	global_load_dword v152, v170, s[34:35]
	global_load_dword v153, v171, s[34:35]
	global_load_dword v154, v172, s[34:35]
	global_load_dword v155, v173, s[34:35]
	global_load_dword v156, v170, s[34:35] offset:2048
	global_load_dword v157, v171, s[34:35] offset:2048
	global_load_dword v158, v172, s[34:35] offset:2048
	global_load_dword v159, v173, s[34:35] offset:2048
	s_waitcnt vmcnt(32)
; __device__ __forceinline__ int crow(int r, int hi) { return (r & 3) + 8 * (r >> 2) + 4 * hi; }
; template <int MODE>
; __device__ __forceinline__ void attn_body(const bf16_t* __restrict__ Qb, const bf16_t* __restrict__ Kh, const bf16_t* __restrict__ Vh, int NT, int krel0,
;                                           char* lds, const float* __restrict__ lutg, const AttnEpi& E) {
;     ...
;     for (int r = 0; r < 16; ++r) { const int row = rowb + crow(r, hi);
;       float ss = 0.f;
; #pragma unroll
;       for (int d0 = 0; d0 < 4; ++d0) { const float c = pk1[(d0 * 16 + r) * 512 + tid] - E.lam * (o[d0][r] * rli[r]); o[d0][r] = c; ss += c * c; }
;       ss += __shfl_xor(ss, 1); ss += __shfl_xor(ss, 2); ss += __shfl_xor(ss, 4); ss += __shfl_xor(ss, 8); ss += __shfl_xor(ss, 16);
;       const float rs = rsqrtf(ss * (1.f / 128.f) + EPS);
	v_mul_f32_e32 v58, v58, v74
	v_fma_f32 v112, -v186, v58, v112
	v_mul_f32_e32 v42, v42, v74
	v_fma_f32 v113, -v186, v42, v113
	v_mul_f32_e32 v26, v26, v74
	v_fma_f32 v114, -v186, v26, v114
	v_mul_f32_e32 v10, v10, v74
	v_fma_f32 v115, -v186, v10, v115
	v_mul_f32_e32 v174, v112, v112
	v_mul_f32_e32 v161, v113, v113
	v_add_f32_e32 v174, v174, v161
	v_mul_f32_e32 v161, v114, v114
	v_add_f32_e32 v174, v174, v161
	v_mul_f32_e32 v161, v115, v115
	v_add_f32_e32 v174, v174, v161
	v_mul_f32_e32 v59, v59, v75
	v_fma_f32 v116, -v186, v59, v116
	v_mul_f32_e32 v43, v43, v75
	v_fma_f32 v117, -v186, v43, v117
	v_mul_f32_e32 v27, v27, v75
	v_fma_f32 v118, -v186, v27, v118
	v_mul_f32_e32 v11, v11, v75
	v_fma_f32 v119, -v186, v11, v119
	v_mul_f32_e32 v175, v116, v116
	v_mul_f32_e32 v161, v117, v117
	v_add_f32_e32 v175, v175, v161
	v_mul_f32_e32 v161, v118, v118
	v_add_f32_e32 v175, v175, v161
	v_mul_f32_e32 v161, v119, v119
	v_add_f32_e32 v175, v175, v161
	v_mul_f32_e32 v60, v60, v76
	v_fma_f32 v120, -v186, v60, v120
	v_mul_f32_e32 v44, v44, v76
	v_fma_f32 v121, -v186, v44, v121
	v_mul_f32_e32 v28, v28, v76
	v_fma_f32 v122, -v186, v28, v122
	v_mul_f32_e32 v12, v12, v76
	v_fma_f32 v123, -v186, v12, v123
	v_mul_f32_e32 v176, v120, v120
	v_mul_f32_e32 v161, v121, v121
	v_add_f32_e32 v176, v176, v161
	v_mul_f32_e32 v161, v122, v122
	v_add_f32_e32 v176, v176, v161
	v_mul_f32_e32 v161, v123, v123
	v_add_f32_e32 v176, v176, v161
	v_mul_f32_e32 v61, v61, v77
	v_fma_f32 v124, -v186, v61, v124
	v_mul_f32_e32 v45, v45, v77
	v_fma_f32 v125, -v186, v45, v125
	v_mul_f32_e32 v29, v29, v77
	v_fma_f32 v126, -v186, v29, v126
	v_mul_f32_e32 v13, v13, v77
	v_fma_f32 v127, -v186, v13, v127
	v_mul_f32_e32 v177, v124, v124
	v_mul_f32_e32 v161, v125, v125
	v_add_f32_e32 v177, v177, v161
	v_mul_f32_e32 v161, v126, v126
	v_add_f32_e32 v177, v177, v161
	v_mul_f32_e32 v161, v127, v127
	v_add_f32_e32 v177, v177, v161
	ds_bpermute_b32 v194, v102, v174
	ds_bpermute_b32 v195, v102, v175
	ds_bpermute_b32 v206, v102, v176
	ds_bpermute_b32 v207, v102, v177
	s_waitcnt lgkmcnt(0)
	v_add_f32_e32 v174, v174, v194
	v_add_f32_e32 v175, v175, v195
	v_add_f32_e32 v176, v176, v206
	v_add_f32_e32 v177, v177, v207
	ds_bpermute_b32 v194, v103, v174
	ds_bpermute_b32 v195, v103, v175
	ds_bpermute_b32 v206, v103, v176
	ds_bpermute_b32 v207, v103, v177
	s_waitcnt lgkmcnt(0)
	v_add_f32_e32 v174, v174, v194
	v_add_f32_e32 v175, v175, v195
	v_add_f32_e32 v176, v176, v206
	v_add_f32_e32 v177, v177, v207
	ds_bpermute_b32 v194, v104, v174
	ds_bpermute_b32 v195, v104, v175
	ds_bpermute_b32 v206, v104, v176
	ds_bpermute_b32 v207, v104, v177
	s_waitcnt lgkmcnt(0)
	v_add_f32_e32 v174, v174, v194
	v_add_f32_e32 v175, v175, v195
	v_add_f32_e32 v176, v176, v206
	v_add_f32_e32 v177, v177, v207
	ds_bpermute_b32 v194, v105, v174
	ds_bpermute_b32 v195, v105, v175
	ds_bpermute_b32 v206, v105, v176
	ds_bpermute_b32 v207, v105, v177
	s_waitcnt lgkmcnt(0)
	v_add_f32_e32 v174, v174, v194
	v_add_f32_e32 v175, v175, v195
	v_add_f32_e32 v176, v176, v206
	v_add_f32_e32 v177, v177, v207
	ds_bpermute_b32 v194, v106, v174
	ds_bpermute_b32 v195, v106, v175
	ds_bpermute_b32 v206, v106, v176
	ds_bpermute_b32 v207, v106, v177
	s_waitcnt lgkmcnt(0)
	v_add_f32_e32 v174, v174, v194
	v_add_f32_e32 v175, v175, v195
	v_add_f32_e32 v176, v176, v206
	v_add_f32_e32 v177, v177, v207
	v_fma_f32 v174, v174, s2, v110
	v_mul_f32_e32 v161, 0x4b800000, v174
	v_cmp_gt_f32_e32 vcc, s49, v174
	s_nop 1
	v_cndmask_b32_e32 v174, v174, v161, vcc
	v_rsq_f32_e32 v174, v174
	s_nop 0
	v_mul_f32_e32 v161, 0x45800000, v174
	v_cndmask_b32_e32 v174, v174, v161, vcc
	v_fma_f32 v175, v175, s2, v110
	v_mul_f32_e32 v161, 0x4b800000, v175
	v_cmp_gt_f32_e32 vcc, s49, v175
	s_nop 1
	v_cndmask_b32_e32 v175, v175, v161, vcc
	v_rsq_f32_e32 v175, v175
	s_nop 0
	v_mul_f32_e32 v161, 0x45800000, v175
	v_cndmask_b32_e32 v175, v175, v161, vcc
	v_fma_f32 v176, v176, s2, v110
	v_mul_f32_e32 v161, 0x4b800000, v176
	v_cmp_gt_f32_e32 vcc, s49, v176
	s_nop 1
	v_cndmask_b32_e32 v176, v176, v161, vcc
	v_rsq_f32_e32 v176, v176
	s_nop 0
	v_mul_f32_e32 v161, 0x45800000, v176
	v_cndmask_b32_e32 v176, v176, v161, vcc
	v_fma_f32 v177, v177, s2, v110
	v_mul_f32_e32 v161, 0x4b800000, v177
	v_cmp_gt_f32_e32 vcc, s49, v177
	s_nop 1
	v_cndmask_b32_e32 v177, v177, v161, vcc
	v_rsq_f32_e32 v177, v177
	s_nop 0
	v_mul_f32_e32 v161, 0x45800000, v177
	v_cndmask_b32_e32 v177, v177, v161, vcc
	s_waitcnt vmcnt(0)
; __device__ __forceinline__ unsigned cvtpk(float lo, float hi) { f32x2 v = {lo, hi}; bf16v2 b = __builtin_convertvector(v, bf16v2); return __builtin_bit_cast(unsigned, b); }
; __device__ __forceinline__ float bf2f(bf16_t v) { return __uint_as_float(((unsigned)v) << 16); }
; template <int MODE>
; __device__ __forceinline__ void attn_body(const bf16_t* __restrict__ Qb, const bf16_t* __restrict__ Kh, const bf16_t* __restrict__ Vh, int NT, int krel0,
;                                           char* lds, const float* __restrict__ lutg, const AttnEpi& E) {
;     ...
;       for (int d0 = 0; d0 < 4; ++d0) { const float c = pk1[(d0 * 16 + r) * 512 + tid] - E.lam * (o[d0][r] * rli[r]); o[d0][r] = c; ss += c * c; }
;       ss += __shfl_xor(ss, 1); ss += __shfl_xor(ss, 2); ss += __shfl_xor(ss, 4); ss += __shfl_xor(ss, 8); ss += __shfl_xor(ss, 16);
;       const float rs = rsqrtf(ss * (1.f / 128.f) + EPS);
; #pragma unroll
;       for (int d0 = 0; d0 < 4; ++d0) { const int col = d0 * 32 + r32;
;         const float g = bf2f(E.gate[(size_t)row * GW + col]);
;         const float y = o[d0][r] * rs * gs[d0] * g + pk0[(d0 * 16 + r) * 512 + tid];
;         E.merged[(size_t)row * DM + col] = (bf16_t)(cvtpk(y, y) & 0xffffu); } }
	v_or_b32_e32 v160, 16, v108
	v_lshl_add_u32 v161, v160, 11, v164
	v_mul_f32_e32 v112, v112, v174
	v_mul_f32_e32 v112, v98, v112
	v_lshlrev_b32_e32 v128, 16, v128
	v_fmac_f32_e32 v144, v112, v128
	v_cvt_pk_bf16_f32 v144, v144, v144
	global_store_short v161, v144, s[6:7]
	v_mul_f32_e32 v113, v113, v174
	v_mul_f32_e32 v113, v99, v113
	v_lshlrev_b32_e32 v129, 16, v129
	v_fmac_f32_e32 v145, v113, v129
	v_cvt_pk_bf16_f32 v145, v145, v145
	global_store_short v161, v145, s[6:7] offset:64
	v_mul_f32_e32 v114, v114, v174
	v_mul_f32_e32 v114, v100, v114
	v_lshlrev_b32_e32 v130, 16, v130
	v_fmac_f32_e32 v146, v114, v130
	v_cvt_pk_bf16_f32 v146, v146, v146
	global_store_short v161, v146, s[6:7] offset:128
	v_mul_f32_e32 v115, v115, v174
	v_mul_f32_e32 v115, v101, v115
	v_lshlrev_b32_e32 v131, 16, v131
	v_fmac_f32_e32 v147, v115, v131
	v_cvt_pk_bf16_f32 v147, v147, v147
	global_store_short v161, v147, s[6:7] offset:192
	v_or_b32_e32 v160, 17, v108
	v_lshl_add_u32 v161, v160, 11, v164
	v_mul_f32_e32 v116, v116, v175
	v_mul_f32_e32 v116, v98, v116
	v_lshlrev_b32_e32 v132, 16, v132
	v_fmac_f32_e32 v148, v116, v132
	v_cvt_pk_bf16_f32 v148, v148, v148
	global_store_short v161, v148, s[6:7]
	v_mul_f32_e32 v117, v117, v175
	v_mul_f32_e32 v117, v99, v117
	v_lshlrev_b32_e32 v133, 16, v133
	v_fmac_f32_e32 v149, v117, v133
	v_cvt_pk_bf16_f32 v149, v149, v149
	global_store_short v161, v149, s[6:7] offset:64
	v_mul_f32_e32 v118, v118, v175
	v_mul_f32_e32 v118, v100, v118
	v_lshlrev_b32_e32 v134, 16, v134
	v_fmac_f32_e32 v150, v118, v134
	v_cvt_pk_bf16_f32 v150, v150, v150
	global_store_short v161, v150, s[6:7] offset:128
	v_mul_f32_e32 v119, v119, v175
	v_mul_f32_e32 v119, v101, v119
	v_lshlrev_b32_e32 v135, 16, v135
	v_fmac_f32_e32 v151, v119, v135
	v_cvt_pk_bf16_f32 v151, v151, v151
	global_store_short v161, v151, s[6:7] offset:192
	v_or_b32_e32 v160, 18, v108
	v_lshl_add_u32 v161, v160, 11, v164
	v_mul_f32_e32 v120, v120, v176
	v_mul_f32_e32 v120, v98, v120
	v_lshlrev_b32_e32 v136, 16, v136
	v_fmac_f32_e32 v152, v120, v136
	v_cvt_pk_bf16_f32 v152, v152, v152
	global_store_short v161, v152, s[6:7]
	v_mul_f32_e32 v121, v121, v176
	v_mul_f32_e32 v121, v99, v121
	v_lshlrev_b32_e32 v137, 16, v137
	v_fmac_f32_e32 v153, v121, v137
	v_cvt_pk_bf16_f32 v153, v153, v153
	global_store_short v161, v153, s[6:7] offset:64
	v_mul_f32_e32 v122, v122, v176
	v_mul_f32_e32 v122, v100, v122
	v_lshlrev_b32_e32 v138, 16, v138
	v_fmac_f32_e32 v154, v122, v138
	v_cvt_pk_bf16_f32 v154, v154, v154
	global_store_short v161, v154, s[6:7] offset:128
	v_mul_f32_e32 v123, v123, v176
	v_mul_f32_e32 v123, v101, v123
	v_lshlrev_b32_e32 v139, 16, v139
	v_fmac_f32_e32 v155, v123, v139
	v_cvt_pk_bf16_f32 v155, v155, v155
	global_store_short v161, v155, s[6:7] offset:192
	v_or_b32_e32 v160, 19, v108
	v_lshl_add_u32 v161, v160, 11, v164
	v_mul_f32_e32 v124, v124, v177
	v_mul_f32_e32 v124, v98, v124
	v_lshlrev_b32_e32 v140, 16, v140
	v_fmac_f32_e32 v156, v124, v140
	v_cvt_pk_bf16_f32 v156, v156, v156
	global_store_short v161, v156, s[6:7]
	v_mul_f32_e32 v125, v125, v177
	v_mul_f32_e32 v125, v99, v125
	v_lshlrev_b32_e32 v141, 16, v141
	v_fmac_f32_e32 v157, v125, v141
	v_cvt_pk_bf16_f32 v157, v157, v157
	global_store_short v161, v157, s[6:7] offset:64
	v_mul_f32_e32 v126, v126, v177
	v_mul_f32_e32 v126, v100, v126
	v_lshlrev_b32_e32 v142, 16, v142
	v_fmac_f32_e32 v158, v126, v142
	v_cvt_pk_bf16_f32 v158, v158, v158
	global_store_short v161, v158, s[6:7] offset:128
	v_mul_f32_e32 v127, v127, v177
	v_mul_f32_e32 v127, v101, v127
	v_lshlrev_b32_e32 v143, 16, v143
	v_fmac_f32_e32 v159, v127, v143
	v_cvt_pk_bf16_f32 v159, v159, v159
	global_store_short v161, v159, s[6:7] offset:192
	v_add_u32_e32 v166, 0x6000, v107
	v_add_u32_e32 v167, 0xe000, v107
	v_add_u32_e32 v168, 0x16000, v107
	v_add_u32_e32 v169, 0x1e000, v107
	v_add_u32_e32 v170, 0x7000, v107
	v_add_u32_e32 v171, 0xf000, v107
	v_add_u32_e32 v172, 0x17000, v107
	v_add_u32_e32 v173, 0x1f000, v107
	global_load_dword v112, v166, s[36:37]
	global_load_dword v113, v167, s[36:37]
	global_load_dword v114, v168, s[36:37]
	global_load_dword v115, v169, s[36:37]
	global_load_dword v116, v166, s[36:37] offset:2048
	global_load_dword v117, v167, s[36:37] offset:2048
	global_load_dword v118, v168, s[36:37] offset:2048
	global_load_dword v119, v169, s[36:37] offset:2048
	global_load_dword v120, v170, s[36:37]
	global_load_dword v121, v171, s[36:37]
	global_load_dword v122, v172, s[36:37]
	global_load_dword v123, v173, s[36:37]
	global_load_dword v124, v170, s[36:37] offset:2048
	global_load_dword v125, v171, s[36:37] offset:2048
	global_load_dword v126, v172, s[36:37] offset:2048
	global_load_dword v127, v173, s[36:37] offset:2048
	v_or_b32_e32 v160, 24, v108
	v_mad_i64_i32 v[190:191], s[28:29], v160, s88, v[162:163]
	global_load_ushort v128, v[190:191], off
	global_load_ushort v129, v[190:191], off offset:64
	global_load_ushort v130, v[190:191], off offset:128
	global_load_ushort v131, v[190:191], off offset:192
	v_or_b32_e32 v160, 25, v108
	v_mad_i64_i32 v[190:191], s[28:29], v160, s88, v[162:163]
	global_load_ushort v132, v[190:191], off
	global_load_ushort v133, v[190:191], off offset:64
	global_load_ushort v134, v[190:191], off offset:128
	global_load_ushort v135, v[190:191], off offset:192
	v_or_b32_e32 v160, 26, v108
	v_mad_i64_i32 v[190:191], s[28:29], v160, s88, v[162:163]
	global_load_ushort v136, v[190:191], off
	global_load_ushort v137, v[190:191], off offset:64
	global_load_ushort v138, v[190:191], off offset:128
	global_load_ushort v139, v[190:191], off offset:192
	v_or_b32_e32 v160, 27, v108
	v_mad_i64_i32 v[190:191], s[28:29], v160, s88, v[162:163]
	global_load_ushort v140, v[190:191], off
	global_load_ushort v141, v[190:191], off offset:64
	global_load_ushort v142, v[190:191], off offset:128
	global_load_ushort v143, v[190:191], off offset:192
	global_load_dword v144, v166, s[34:35]
	global_load_dword v145, v167, s[34:35]
	global_load_dword v146, v168, s[34:35]
	global_load_dword v147, v169, s[34:35]
	global_load_dword v148, v166, s[34:35] offset:2048
	global_load_dword v149, v167, s[34:35] offset:2048
	global_load_dword v150, v168, s[34:35] offset:2048
	global_load_dword v151, v169, s[34:35] offset:2048
	global_load_dword v152, v170, s[34:35]
	global_load_dword v153, v171, s[34:35]
	global_load_dword v154, v172, s[34:35]
	global_load_dword v155, v173, s[34:35]
	global_load_dword v156, v170, s[34:35] offset:2048
	global_load_dword v157, v171, s[34:35] offset:2048
	global_load_dword v158, v172, s[34:35] offset:2048
	global_load_dword v159, v173, s[34:35] offset:2048
	s_waitcnt vmcnt(32)
; __device__ __forceinline__ int crow(int r, int hi) { return (r & 3) + 8 * (r >> 2) + 4 * hi; }
; template <int MODE>
; __device__ __forceinline__ void attn_body(const bf16_t* __restrict__ Qb, const bf16_t* __restrict__ Kh, const bf16_t* __restrict__ Vh, int NT, int krel0,
;                                           char* lds, const float* __restrict__ lutg, const AttnEpi& E) {
;     ...
;     for (int r = 0; r < 16; ++r) { const int row = rowb + crow(r, hi);
;       float ss = 0.f;
; #pragma unroll
;       for (int d0 = 0; d0 < 4; ++d0) { const float c = pk1[(d0 * 16 + r) * 512 + tid] - E.lam * (o[d0][r] * rli[r]); o[d0][r] = c; ss += c * c; }
;       ss += __shfl_xor(ss, 1); ss += __shfl_xor(ss, 2); ss += __shfl_xor(ss, 4); ss += __shfl_xor(ss, 8); ss += __shfl_xor(ss, 16);
;       const float rs = rsqrtf(ss * (1.f / 128.f) + EPS);
	v_mul_f32_e32 v62, v62, v78
	v_fma_f32 v112, -v186, v62, v112
	v_mul_f32_e32 v46, v46, v78
	v_fma_f32 v113, -v186, v46, v113
	v_mul_f32_e32 v30, v30, v78
	v_fma_f32 v114, -v186, v30, v114
	v_mul_f32_e32 v14, v14, v78
	v_fma_f32 v115, -v186, v14, v115
	v_mul_f32_e32 v174, v112, v112
	v_mul_f32_e32 v161, v113, v113
	v_add_f32_e32 v174, v174, v161
	v_mul_f32_e32 v161, v114, v114
	v_add_f32_e32 v174, v174, v161
	v_mul_f32_e32 v161, v115, v115
	v_add_f32_e32 v174, v174, v161
	v_mul_f32_e32 v63, v63, v79
	v_fma_f32 v116, -v186, v63, v116
	v_mul_f32_e32 v47, v47, v79
	v_fma_f32 v117, -v186, v47, v117
	v_mul_f32_e32 v31, v31, v79
	v_fma_f32 v118, -v186, v31, v118
	v_mul_f32_e32 v15, v15, v79
	v_fma_f32 v119, -v186, v15, v119
	v_mul_f32_e32 v175, v116, v116
	v_mul_f32_e32 v161, v117, v117
	v_add_f32_e32 v175, v175, v161
	v_mul_f32_e32 v161, v118, v118
	v_add_f32_e32 v175, v175, v161
	v_mul_f32_e32 v161, v119, v119
	v_add_f32_e32 v175, v175, v161
	v_mul_f32_e32 v64, v64, v80
	v_fma_f32 v120, -v186, v64, v120
	v_mul_f32_e32 v48, v48, v80
	v_fma_f32 v121, -v186, v48, v121
	v_mul_f32_e32 v32, v32, v80
	v_fma_f32 v122, -v186, v32, v122
	v_mul_f32_e32 v16, v16, v80
	v_fma_f32 v123, -v186, v16, v123
	v_mul_f32_e32 v176, v120, v120
	v_mul_f32_e32 v161, v121, v121
	v_add_f32_e32 v176, v176, v161
	v_mul_f32_e32 v161, v122, v122
	v_add_f32_e32 v176, v176, v161
	v_mul_f32_e32 v161, v123, v123
	v_add_f32_e32 v176, v176, v161
	v_mul_f32_e32 v65, v65, v81
	v_fma_f32 v124, -v186, v65, v124
	v_mul_f32_e32 v49, v49, v81
	v_fma_f32 v125, -v186, v49, v125
	v_mul_f32_e32 v33, v33, v81
	v_fma_f32 v126, -v186, v33, v126
	v_mul_f32_e32 v17, v17, v81
	v_fma_f32 v127, -v186, v17, v127
	v_mul_f32_e32 v177, v124, v124
	v_mul_f32_e32 v161, v125, v125
	v_add_f32_e32 v177, v177, v161
	v_mul_f32_e32 v161, v126, v126
	v_add_f32_e32 v177, v177, v161
	v_mul_f32_e32 v161, v127, v127
	v_add_f32_e32 v177, v177, v161
	ds_bpermute_b32 v194, v102, v174
	ds_bpermute_b32 v195, v102, v175
	ds_bpermute_b32 v206, v102, v176
	ds_bpermute_b32 v207, v102, v177
	s_waitcnt lgkmcnt(0)
	v_add_f32_e32 v174, v174, v194
	v_add_f32_e32 v175, v175, v195
	v_add_f32_e32 v176, v176, v206
	v_add_f32_e32 v177, v177, v207
	ds_bpermute_b32 v194, v103, v174
	ds_bpermute_b32 v195, v103, v175
	ds_bpermute_b32 v206, v103, v176
	ds_bpermute_b32 v207, v103, v177
	s_waitcnt lgkmcnt(0)
	v_add_f32_e32 v174, v174, v194
	v_add_f32_e32 v175, v175, v195
	v_add_f32_e32 v176, v176, v206
	v_add_f32_e32 v177, v177, v207
	ds_bpermute_b32 v194, v104, v174
	ds_bpermute_b32 v195, v104, v175
	ds_bpermute_b32 v206, v104, v176
	ds_bpermute_b32 v207, v104, v177
	s_waitcnt lgkmcnt(0)
	v_add_f32_e32 v174, v174, v194
	v_add_f32_e32 v175, v175, v195
	v_add_f32_e32 v176, v176, v206
	v_add_f32_e32 v177, v177, v207
	ds_bpermute_b32 v194, v105, v174
	ds_bpermute_b32 v195, v105, v175
	ds_bpermute_b32 v206, v105, v176
	ds_bpermute_b32 v207, v105, v177
	s_waitcnt lgkmcnt(0)
	v_add_f32_e32 v174, v174, v194
	v_add_f32_e32 v175, v175, v195
	v_add_f32_e32 v176, v176, v206
	v_add_f32_e32 v177, v177, v207
	ds_bpermute_b32 v194, v106, v174
	ds_bpermute_b32 v195, v106, v175
	ds_bpermute_b32 v206, v106, v176
	ds_bpermute_b32 v207, v106, v177
	s_waitcnt lgkmcnt(0)
	v_add_f32_e32 v174, v174, v194
	v_add_f32_e32 v175, v175, v195
	v_add_f32_e32 v176, v176, v206
	v_add_f32_e32 v177, v177, v207
	v_fma_f32 v174, v174, s2, v110
	v_mul_f32_e32 v161, 0x4b800000, v174
	v_cmp_gt_f32_e32 vcc, s49, v174
	s_nop 1
	v_cndmask_b32_e32 v174, v174, v161, vcc
	v_rsq_f32_e32 v174, v174
	s_nop 0
	v_mul_f32_e32 v161, 0x45800000, v174
	v_cndmask_b32_e32 v174, v174, v161, vcc
	v_fma_f32 v175, v175, s2, v110
	v_mul_f32_e32 v161, 0x4b800000, v175
	v_cmp_gt_f32_e32 vcc, s49, v175
	s_nop 1
	v_cndmask_b32_e32 v175, v175, v161, vcc
	v_rsq_f32_e32 v175, v175
	s_nop 0
	v_mul_f32_e32 v161, 0x45800000, v175
	v_cndmask_b32_e32 v175, v175, v161, vcc
	v_fma_f32 v176, v176, s2, v110
	v_mul_f32_e32 v161, 0x4b800000, v176
	v_cmp_gt_f32_e32 vcc, s49, v176
	s_nop 1
	v_cndmask_b32_e32 v176, v176, v161, vcc
	v_rsq_f32_e32 v176, v176
	s_nop 0
	v_mul_f32_e32 v161, 0x45800000, v176
	v_cndmask_b32_e32 v176, v176, v161, vcc
	v_fma_f32 v177, v177, s2, v110
	v_mul_f32_e32 v161, 0x4b800000, v177
	v_cmp_gt_f32_e32 vcc, s49, v177
	s_nop 1
	v_cndmask_b32_e32 v177, v177, v161, vcc
	v_rsq_f32_e32 v177, v177
	s_nop 0
	v_mul_f32_e32 v161, 0x45800000, v177
	v_cndmask_b32_e32 v177, v177, v161, vcc
	s_waitcnt vmcnt(0)
; __device__ __forceinline__ unsigned cvtpk(float lo, float hi) { f32x2 v = {lo, hi}; bf16v2 b = __builtin_convertvector(v, bf16v2); return __builtin_bit_cast(unsigned, b); }
; __device__ __forceinline__ float bf2f(bf16_t v) { return __uint_as_float(((unsigned)v) << 16); }
; template <int MODE>
; __device__ __forceinline__ void attn_body(const bf16_t* __restrict__ Qb, const bf16_t* __restrict__ Kh, const bf16_t* __restrict__ Vh, int NT, int krel0,
;                                           char* lds, const float* __restrict__ lutg, const AttnEpi& E) {
;     ...
; #pragma unroll
;       for (int d0 = 0; d0 < 4; ++d0) { const int col = d0 * 32 + r32;
;         const float g = bf2f(E.gate[(size_t)row * GW + col]);
;         const float y = o[d0][r] * rs * gs[d0] * g + pk0[(d0 * 16 + r) * 512 + tid];
;         E.merged[(size_t)row * DM + col] = (bf16_t)(cvtpk(y, y) & 0xffffu); } }
	v_or_b32_e32 v160, 24, v108
	v_lshl_add_u32 v161, v160, 11, v164
	v_mul_f32_e32 v112, v112, v174
	v_mul_f32_e32 v112, v98, v112
	v_lshlrev_b32_e32 v128, 16, v128
	v_fmac_f32_e32 v144, v112, v128
	v_cvt_pk_bf16_f32 v144, v144, v144
	global_store_short v161, v144, s[6:7]
	v_mul_f32_e32 v113, v113, v174
	v_mul_f32_e32 v113, v99, v113
	v_lshlrev_b32_e32 v129, 16, v129
	v_fmac_f32_e32 v145, v113, v129
	v_cvt_pk_bf16_f32 v145, v145, v145
	global_store_short v161, v145, s[6:7] offset:64
	v_mul_f32_e32 v114, v114, v174
	v_mul_f32_e32 v114, v100, v114
	v_lshlrev_b32_e32 v130, 16, v130
	v_fmac_f32_e32 v146, v114, v130
	v_cvt_pk_bf16_f32 v146, v146, v146
	global_store_short v161, v146, s[6:7] offset:128
	v_mul_f32_e32 v115, v115, v174
	v_mul_f32_e32 v115, v101, v115
	v_lshlrev_b32_e32 v131, 16, v131
	v_fmac_f32_e32 v147, v115, v131
	v_cvt_pk_bf16_f32 v147, v147, v147
	global_store_short v161, v147, s[6:7] offset:192
	v_or_b32_e32 v160, 25, v108
	v_lshl_add_u32 v161, v160, 11, v164
	v_mul_f32_e32 v116, v116, v175
	v_mul_f32_e32 v116, v98, v116
	v_lshlrev_b32_e32 v132, 16, v132
	v_fmac_f32_e32 v148, v116, v132
	v_cvt_pk_bf16_f32 v148, v148, v148
	global_store_short v161, v148, s[6:7]
	v_mul_f32_e32 v117, v117, v175
	v_mul_f32_e32 v117, v99, v117
	v_lshlrev_b32_e32 v133, 16, v133
	v_fmac_f32_e32 v149, v117, v133
	v_cvt_pk_bf16_f32 v149, v149, v149
	global_store_short v161, v149, s[6:7] offset:64
	v_mul_f32_e32 v118, v118, v175
	v_mul_f32_e32 v118, v100, v118
	v_lshlrev_b32_e32 v134, 16, v134
	v_fmac_f32_e32 v150, v118, v134
	v_cvt_pk_bf16_f32 v150, v150, v150
	global_store_short v161, v150, s[6:7] offset:128
	v_mul_f32_e32 v119, v119, v175
	v_mul_f32_e32 v119, v101, v119
	v_lshlrev_b32_e32 v135, 16, v135
	v_fmac_f32_e32 v151, v119, v135
	v_cvt_pk_bf16_f32 v151, v151, v151
	global_store_short v161, v151, s[6:7] offset:192
	v_or_b32_e32 v160, 26, v108
	v_lshl_add_u32 v161, v160, 11, v164
	v_mul_f32_e32 v120, v120, v176
	v_mul_f32_e32 v120, v98, v120
	v_lshlrev_b32_e32 v136, 16, v136
	v_fmac_f32_e32 v152, v120, v136
	v_cvt_pk_bf16_f32 v152, v152, v152
	global_store_short v161, v152, s[6:7]
	v_mul_f32_e32 v121, v121, v176
	v_mul_f32_e32 v121, v99, v121
	v_lshlrev_b32_e32 v137, 16, v137
	v_fmac_f32_e32 v153, v121, v137
	v_cvt_pk_bf16_f32 v153, v153, v153
	global_store_short v161, v153, s[6:7] offset:64
	v_mul_f32_e32 v122, v122, v176
	v_mul_f32_e32 v122, v100, v122
	v_lshlrev_b32_e32 v138, 16, v138
	v_fmac_f32_e32 v154, v122, v138
	v_cvt_pk_bf16_f32 v154, v154, v154
	global_store_short v161, v154, s[6:7] offset:128
	v_mul_f32_e32 v123, v123, v176
	v_mul_f32_e32 v123, v101, v123
	v_lshlrev_b32_e32 v139, 16, v139
	v_fmac_f32_e32 v155, v123, v139
	v_cvt_pk_bf16_f32 v155, v155, v155
	global_store_short v161, v155, s[6:7] offset:192
	v_or_b32_e32 v160, 27, v108
	v_lshl_add_u32 v161, v160, 11, v164
	v_mul_f32_e32 v124, v124, v177
	v_mul_f32_e32 v124, v98, v124
	v_lshlrev_b32_e32 v140, 16, v140
	v_fmac_f32_e32 v156, v124, v140
	v_cvt_pk_bf16_f32 v156, v156, v156
	global_store_short v161, v156, s[6:7]
	v_mul_f32_e32 v125, v125, v177
	v_mul_f32_e32 v125, v99, v125
	v_lshlrev_b32_e32 v141, 16, v141
	v_fmac_f32_e32 v157, v125, v141
	v_cvt_pk_bf16_f32 v157, v157, v157
	global_store_short v161, v157, s[6:7] offset:64
	v_mul_f32_e32 v126, v126, v177
	v_mul_f32_e32 v126, v100, v126
	v_lshlrev_b32_e32 v142, 16, v142
	v_fmac_f32_e32 v158, v126, v142
	v_cvt_pk_bf16_f32 v158, v158, v158
	global_store_short v161, v158, s[6:7] offset:128
	v_mul_f32_e32 v127, v127, v177
	v_mul_f32_e32 v127, v101, v127
	v_lshlrev_b32_e32 v143, 16, v143
	v_fmac_f32_e32 v159, v127, v143
	v_cvt_pk_bf16_f32 v159, v159, v159
	global_store_short v161, v159, s[6:7] offset:192
	s_cmpk_gt_i32 s10, 0x3ff
	s_cbranch_scc1 .LBB0_213

;     __device__ __forceinline__ void operator()(const f32x4 (&acc)[2][2][4][2], const Unit& u, int wr, int wc, int fr, int fq) const {
;         const int row0 = u.pm * BM + wr * 64 + fr, col0 = u.pn * BM + wc * 32 + 4 * fq;
;         const float* Rb = u.pm < 64 ? R0 : R1;
;         const int bi = u.pm < 64 ? (u.pm >> 3) : 8;
;         const float* mg = modg + (size_t)bi * 9216 + col0;
;         f32x4 gv[2][2];
; #pragma unroll
;         for (int bj = 0; bj < 2; ++bj)
; #pragma unroll
;             for (int n = 0; n < 2; ++n) gv[bj][n] = *(const f32x4*)(mg + bj * HALF + n * 16) * gs;
; #pragma unroll
;         for (int ai = 0; ai < 2; ++ai)
; #pragma unroll
;             for (int m = 0; m < 4; ++m) { float* rowp = X + (size_t)(row0 + ai * HALF + m * 16) * DM + col0;
; #pragma unroll
;                 for (int bj = 0; bj < 2; ++bj)
; #pragma unroll
;                     for (int n = 0; n < 2; ++n) { f32x4* q = (f32x4*)(rowp + bj * HALF + n * 16); const f32x4* rq = (const f32x4*)(Rb + (q - (f32x4*)X) * 4); *q = *rq + gv[bj][n] * acc[ai][bj][m][n]; } }
;     }
.LBB0_219:
	s_and_b64 s[42:43], s[56:57], exec
	s_cselect_b32 s57, s75, s77
	s_cselect_b32 s56, s76, s78
	v_lshl_or_b32 v140, s89, 8, v164
	s_lshl_b64 s[42:43], s[58:59], 2
	s_add_u32 s42, s73, s42
	v_ashrrev_i32_e32 v141, 31, v140
	s_addc_u32 s43, s74, s43
	v_lshlrev_b64 v[156:157], 2, v[140:141]
	v_lshl_add_u64 v[158:159], s[42:43], 0, v[156:157]
	global_load_dwordx4 v[140:143], v[158:159], off
	global_load_dwordx4 v[166:169], v[158:159], off offset:576
	v_mov_b32_e32 v133, v132
	v_lshl_add_u32 v160, s13, 8, v162
	v_ashrrev_i32_e32 v161, 31, v160
	s_mov_b64 s[42:43], 0x80000
	s_and_b64 vcc, exec, s[6:7]
	s_mov_b32 s89, s12
	s_mov_b32 s13, s93
	s_mov_b64 s[58:59], s[10:11]
	s_waitcnt vmcnt(0)
	v_pk_mul_f32 v[152:153], v[142:143], v[132:133]
	v_pk_mul_f32 v[154:155], v[140:141], v[134:135]
	global_load_dwordx4 v[140:143], v[158:159], off offset:64
	s_waitcnt vmcnt(0)
	v_pk_mul_f32 v[148:149], v[132:133], v[142:143]
	v_pk_mul_f32 v[150:151], v[134:135], v[140:141]
	global_load_dwordx4 v[140:143], v[158:159], off offset:512
	v_lshlrev_b64 v[158:159], 12, v[160:161]
	s_waitcnt vmcnt(0)
	v_pk_mul_f32 v[144:145], v[132:133], v[142:143]
	v_pk_mul_f32 v[142:143], v[134:135], v[166:167]
	v_lshl_add_u64 v[166:167], s[84:85], 0, v[158:159]
	v_lshl_add_u64 v[170:171], v[166:167], 0, v[156:157]
	v_lshl_add_u64 v[166:167], s[56:57], 0, v[158:159]
	v_lshl_add_u64 v[172:173], v[166:167], 0, v[156:157]
	v_pk_mul_f32 v[146:147], v[134:135], v[140:141]
	v_pk_mul_f32 v[140:141], v[132:133], v[168:169]
	global_load_dwordx4 v[204:207], v[172:173], off
	global_load_dwordx4 v[208:211], v[172:173], off offset:64
	global_load_dwordx4 v[212:215], v[172:173], off offset:512
	global_load_dwordx4 v[216:219], v[172:173], off offset:576
	s_waitcnt vmcnt(3)
	v_pk_fma_f32 v[128:129], v[128:129], v[152:153], v[206:207]
	v_pk_fma_f32 v[126:127], v[126:127], v[154:155], v[204:205]
	global_store_dwordx4 v[170:171], v[126:129], off
	s_waitcnt vmcnt(3)
	v_pk_fma_f32 v[124:125], v[124:125], v[148:149], v[210:211]
	v_pk_fma_f32 v[122:123], v[122:123], v[150:151], v[208:209]
	global_store_dwordx4 v[170:171], v[122:125], off offset:64
	s_waitcnt vmcnt(3)
	v_pk_fma_f32 v[120:121], v[120:121], v[144:145], v[214:215]
	v_pk_fma_f32 v[118:119], v[118:119], v[146:147], v[212:213]
	global_store_dwordx4 v[170:171], v[118:121], off offset:512
	s_waitcnt vmcnt(3)
	v_pk_fma_f32 v[116:117], v[116:117], v[140:141], v[218:219]
	v_pk_fma_f32 v[114:115], v[114:115], v[142:143], v[216:217]
	global_store_dwordx4 v[170:171], v[114:117], off offset:576
	s_nop 1
	v_or_b32_e32 v114, 16, v160
	v_ashrrev_i32_e32 v115, 31, v114
	v_lshlrev_b64 v[114:115], 12, v[114:115]
	v_lshl_add_u64 v[116:117], s[84:85], 0, v[114:115]
	v_lshl_add_u64 v[114:115], s[56:57], 0, v[114:115]
	v_lshl_add_u64 v[120:121], v[114:115], 0, v[156:157]
	v_lshl_add_u64 v[118:119], v[116:117], 0, v[156:157]
	global_load_dwordx4 v[226:229], v[120:121], off
	global_load_dwordx4 v[230:233], v[120:121], off offset:64
	global_load_dwordx4 v[234:237], v[120:121], off offset:512
	global_load_dwordx4 v[238:241], v[120:121], off offset:576
	s_waitcnt vmcnt(3)
	v_pk_fma_f32 v[112:113], v[112:113], v[152:153], v[228:229]
	v_pk_fma_f32 v[110:111], v[110:111], v[154:155], v[226:227]
	global_store_dwordx4 v[118:119], v[110:113], off
	s_waitcnt vmcnt(3)
	v_pk_fma_f32 v[108:109], v[108:109], v[148:149], v[232:233]
	v_pk_fma_f32 v[106:107], v[106:107], v[150:151], v[230:231]
	global_store_dwordx4 v[118:119], v[106:109], off offset:64
	s_waitcnt vmcnt(3)
	v_pk_fma_f32 v[104:105], v[104:105], v[144:145], v[236:237]
	v_pk_fma_f32 v[102:103], v[102:103], v[146:147], v[234:235]
	global_store_dwordx4 v[118:119], v[102:105], off offset:512
	s_waitcnt vmcnt(3)
	v_pk_fma_f32 v[100:101], v[100:101], v[140:141], v[240:241]
	v_pk_fma_f32 v[98:99], v[98:99], v[142:143], v[238:239]
	global_store_dwordx4 v[118:119], v[98:101], off offset:576
	s_nop 1
	v_or_b32_e32 v98, 32, v160
	v_ashrrev_i32_e32 v99, 31, v98
	v_lshlrev_b64 v[98:99], 12, v[98:99]
	v_lshl_add_u64 v[100:101], s[84:85], 0, v[98:99]
	v_lshl_add_u64 v[98:99], s[56:57], 0, v[98:99]
	v_lshl_add_u64 v[104:105], v[98:99], 0, v[156:157]
	v_lshl_add_u64 v[102:103], v[100:101], 0, v[156:157]
	global_load_dwordx4 v[204:207], v[104:105], off
	global_load_dwordx4 v[208:211], v[104:105], off offset:64
	global_load_dwordx4 v[212:215], v[104:105], off offset:512
	global_load_dwordx4 v[216:219], v[104:105], off offset:576
	s_waitcnt vmcnt(3)
	v_pk_fma_f32 v[96:97], v[96:97], v[152:153], v[206:207]
	v_pk_fma_f32 v[94:95], v[94:95], v[154:155], v[204:205]
	global_store_dwordx4 v[102:103], v[94:97], off
	s_waitcnt vmcnt(3)
	v_pk_fma_f32 v[92:93], v[92:93], v[148:149], v[210:211]
	v_pk_fma_f32 v[90:91], v[90:91], v[150:151], v[208:209]
	global_store_dwordx4 v[102:103], v[90:93], off offset:64
	s_waitcnt vmcnt(3)
	v_pk_fma_f32 v[88:89], v[88:89], v[144:145], v[214:215]
	v_pk_fma_f32 v[86:87], v[86:87], v[146:147], v[212:213]
	global_store_dwordx4 v[102:103], v[86:89], off offset:512
	s_waitcnt vmcnt(3)
	v_pk_fma_f32 v[84:85], v[84:85], v[140:141], v[218:219]
	v_pk_fma_f32 v[82:83], v[82:83], v[142:143], v[216:217]
	global_store_dwordx4 v[102:103], v[82:85], off offset:576
	s_nop 1
	v_or_b32_e32 v82, 48, v160
	v_ashrrev_i32_e32 v83, 31, v82
	v_lshlrev_b64 v[82:83], 12, v[82:83]
	v_lshl_add_u64 v[84:85], s[84:85], 0, v[82:83]
	v_lshl_add_u64 v[82:83], s[56:57], 0, v[82:83]
	v_lshl_add_u64 v[88:89], v[82:83], 0, v[156:157]
	v_lshl_add_u64 v[86:87], v[84:85], 0, v[156:157]
	global_load_dwordx4 v[226:229], v[88:89], off
	global_load_dwordx4 v[230:233], v[88:89], off offset:64
	global_load_dwordx4 v[234:237], v[88:89], off offset:512
	global_load_dwordx4 v[238:241], v[88:89], off offset:576
	s_waitcnt vmcnt(3)
;     __device__ __forceinline__ void operator()(const f32x4 (&acc)[2][2][4][2], const Unit& u, int wr, int wc, int fr, int fq) const {
;         const int row0 = u.pm * BM + wr * 64 + fr, col0 = u.pn * BM + wc * 32 + 4 * fq;
;         const float* Rb = u.pm < 64 ? R0 : R1;
;         const int bi = u.pm < 64 ? (u.pm >> 3) : 8;
;         const float* mg = modg + (size_t)bi * 9216 + col0;
;         f32x4 gv[2][2];
; #pragma unroll
;         for (int bj = 0; bj < 2; ++bj)
; #pragma unroll
;             for (int n = 0; n < 2; ++n) gv[bj][n] = *(const f32x4*)(mg + bj * HALF + n * 16) * gs;
; #pragma unroll
;         for (int ai = 0; ai < 2; ++ai)
; #pragma unroll
;             for (int m = 0; m < 4; ++m) { float* rowp = X + (size_t)(row0 + ai * HALF + m * 16) * DM + col0;
; #pragma unroll
;                 for (int bj = 0; bj < 2; ++bj)
; #pragma unroll
;                     for (int n = 0; n < 2; ++n) { f32x4* q = (f32x4*)(rowp + bj * HALF + n * 16); const f32x4* rq = (const f32x4*)(Rb + (q - (f32x4*)X) * 4); *q = *rq + gv[bj][n] * acc[ai][bj][m][n]; } }
;     }
	v_pk_fma_f32 v[80:81], v[80:81], v[152:153], v[228:229]
	v_pk_fma_f32 v[78:79], v[78:79], v[154:155], v[226:227]
	global_store_dwordx4 v[86:87], v[78:81], off
	s_waitcnt vmcnt(3)
	v_pk_fma_f32 v[76:77], v[76:77], v[148:149], v[232:233]
	v_pk_fma_f32 v[74:75], v[74:75], v[150:151], v[230:231]
	global_store_dwordx4 v[86:87], v[74:77], off offset:64
	s_waitcnt vmcnt(3)
	v_pk_fma_f32 v[72:73], v[72:73], v[144:145], v[236:237]
	v_pk_fma_f32 v[70:71], v[70:71], v[146:147], v[234:235]
	global_store_dwordx4 v[86:87], v[70:73], off offset:512
	s_waitcnt vmcnt(3)
	v_pk_fma_f32 v[68:69], v[68:69], v[140:141], v[240:241]
	v_pk_fma_f32 v[66:67], v[66:67], v[142:143], v[238:239]
	global_store_dwordx4 v[86:87], v[66:69], off offset:576
	s_nop 1
	v_lshl_add_u64 v[66:67], v[158:159], 0, s[42:43]
	v_lshl_add_u64 v[68:69], s[84:85], 0, v[66:67]
	v_lshl_add_u64 v[66:67], s[56:57], 0, v[66:67]
	v_lshl_add_u64 v[72:73], v[66:67], 0, v[156:157]
	v_lshl_add_u64 v[70:71], v[68:69], 0, v[156:157]
	s_mov_b64 s[42:43], 0x90000
	global_load_dwordx4 v[204:207], v[72:73], off
	global_load_dwordx4 v[208:211], v[72:73], off offset:64
	global_load_dwordx4 v[212:215], v[72:73], off offset:512
	global_load_dwordx4 v[216:219], v[72:73], off offset:576
	s_waitcnt vmcnt(3)
	v_pk_fma_f32 v[64:65], v[64:65], v[152:153], v[206:207]
	v_pk_fma_f32 v[62:63], v[62:63], v[154:155], v[204:205]
	global_store_dwordx4 v[70:71], v[62:65], off
	s_waitcnt vmcnt(3)
	v_pk_fma_f32 v[60:61], v[60:61], v[148:149], v[210:211]
	v_pk_fma_f32 v[58:59], v[58:59], v[150:151], v[208:209]
	global_store_dwordx4 v[70:71], v[58:61], off offset:64
	s_waitcnt vmcnt(3)
	v_pk_fma_f32 v[56:57], v[56:57], v[144:145], v[214:215]
	v_pk_fma_f32 v[54:55], v[54:55], v[146:147], v[212:213]
	global_store_dwordx4 v[70:71], v[54:57], off offset:512
	s_waitcnt vmcnt(3)
	v_pk_fma_f32 v[52:53], v[52:53], v[140:141], v[218:219]
	v_pk_fma_f32 v[50:51], v[50:51], v[142:143], v[216:217]
	global_store_dwordx4 v[70:71], v[50:53], off offset:576
	s_nop 1
	v_lshl_add_u64 v[50:51], v[158:159], 0, s[42:43]
	v_lshl_add_u64 v[52:53], s[84:85], 0, v[50:51]
	v_lshl_add_u64 v[50:51], s[56:57], 0, v[50:51]
	v_lshl_add_u64 v[56:57], v[50:51], 0, v[156:157]
	v_lshl_add_u64 v[54:55], v[52:53], 0, v[156:157]
	s_mov_b64 s[42:43], 0xa0000
	global_load_dwordx4 v[226:229], v[56:57], off
	global_load_dwordx4 v[230:233], v[56:57], off offset:64
	global_load_dwordx4 v[234:237], v[56:57], off offset:512
	global_load_dwordx4 v[238:241], v[56:57], off offset:576
	s_waitcnt vmcnt(3)
	v_pk_fma_f32 v[48:49], v[48:49], v[152:153], v[228:229]
	v_pk_fma_f32 v[46:47], v[46:47], v[154:155], v[226:227]
	global_store_dwordx4 v[54:55], v[46:49], off
	s_waitcnt vmcnt(3)
	v_pk_fma_f32 v[44:45], v[44:45], v[148:149], v[232:233]
	v_pk_fma_f32 v[42:43], v[42:43], v[150:151], v[230:231]
	global_store_dwordx4 v[54:55], v[42:45], off offset:64
	s_waitcnt vmcnt(3)
	v_pk_fma_f32 v[40:41], v[40:41], v[144:145], v[236:237]
	v_pk_fma_f32 v[38:39], v[38:39], v[146:147], v[234:235]
	global_store_dwordx4 v[54:55], v[38:41], off offset:512
	s_waitcnt vmcnt(3)
	v_pk_fma_f32 v[36:37], v[36:37], v[140:141], v[240:241]
	v_pk_fma_f32 v[34:35], v[34:35], v[142:143], v[238:239]
	global_store_dwordx4 v[54:55], v[34:37], off offset:576
	s_nop 1
	v_lshl_add_u64 v[34:35], v[158:159], 0, s[42:43]
	v_lshl_add_u64 v[36:37], s[84:85], 0, v[34:35]
	v_lshl_add_u64 v[34:35], s[56:57], 0, v[34:35]
	v_lshl_add_u64 v[40:41], v[34:35], 0, v[156:157]
	v_lshl_add_u64 v[38:39], v[36:37], 0, v[156:157]
	s_mov_b64 s[42:43], 0xb0000
	global_load_dwordx4 v[204:207], v[40:41], off
	global_load_dwordx4 v[208:211], v[40:41], off offset:64
	global_load_dwordx4 v[212:215], v[40:41], off offset:512
	global_load_dwordx4 v[216:219], v[40:41], off offset:576
	s_waitcnt vmcnt(3)
	v_pk_fma_f32 v[32:33], v[32:33], v[152:153], v[206:207]
	v_pk_fma_f32 v[30:31], v[30:31], v[154:155], v[204:205]
	global_store_dwordx4 v[38:39], v[30:33], off
	s_waitcnt vmcnt(3)
	v_pk_fma_f32 v[28:29], v[28:29], v[148:149], v[210:211]
	v_pk_fma_f32 v[26:27], v[26:27], v[150:151], v[208:209]
	global_store_dwordx4 v[38:39], v[26:29], off offset:64
	s_waitcnt vmcnt(3)
	v_pk_fma_f32 v[24:25], v[24:25], v[144:145], v[214:215]
	v_pk_fma_f32 v[22:23], v[22:23], v[146:147], v[212:213]
	global_store_dwordx4 v[38:39], v[22:25], off offset:512
	s_waitcnt vmcnt(3)
	v_pk_fma_f32 v[20:21], v[20:21], v[140:141], v[218:219]
	v_pk_fma_f32 v[18:19], v[18:19], v[142:143], v[216:217]
	global_store_dwordx4 v[38:39], v[18:21], off offset:576
	s_nop 1
	v_lshl_add_u64 v[18:19], v[158:159], 0, s[42:43]
	v_lshl_add_u64 v[20:21], s[84:85], 0, v[18:19]
	v_lshl_add_u64 v[18:19], s[56:57], 0, v[18:19]
	v_lshl_add_u64 v[24:25], v[18:19], 0, v[156:157]
	v_lshl_add_u64 v[22:23], v[20:21], 0, v[156:157]
	s_mov_b64 s[56:57], s[0:1]
	global_load_dwordx4 v[226:229], v[24:25], off
	global_load_dwordx4 v[230:233], v[24:25], off offset:64
	global_load_dwordx4 v[234:237], v[24:25], off offset:512
	global_load_dwordx4 v[238:241], v[24:25], off offset:576
	s_waitcnt vmcnt(3)
	v_pk_fma_f32 v[16:17], v[16:17], v[152:153], v[228:229]
	v_pk_fma_f32 v[14:15], v[14:15], v[154:155], v[226:227]
	global_store_dwordx4 v[22:23], v[14:17], off
	s_waitcnt vmcnt(3)
	v_pk_fma_f32 v[12:13], v[12:13], v[148:149], v[232:233]
	v_pk_fma_f32 v[10:11], v[10:11], v[150:151], v[230:231]
	global_store_dwordx4 v[22:23], v[10:13], off offset:64
	s_waitcnt vmcnt(3)
	v_pk_fma_f32 v[8:9], v[8:9], v[144:145], v[236:237]
	v_pk_fma_f32 v[6:7], v[6:7], v[146:147], v[234:235]
	global_store_dwordx4 v[22:23], v[6:9], off offset:512
	s_waitcnt vmcnt(3)
	v_pk_fma_f32 v[4:5], v[4:5], v[140:141], v[240:241]
	v_pk_fma_f32 v[2:3], v[2:3], v[142:143], v[238:239]
	global_store_dwordx4 v[22:23], v[2:5], off offset:576
	s_cbranch_vccnz .LBB0_234
